# GEMM K-loops: also removed the back-to-back s_setprio 0 / s_setprio 1 pair inside each 32-MFMA block (two issue slots in the MFMA stream, four times per iteration)
# speedup vs baseline: 1.0253x; 1.0065x over previous
; #define PG8_STAGE(bufoff, gbase, voff) do { _Pragma("unroll") for (int _i = 0; _i < 2; ++_i) \
;         __builtin_amdgcn_global_load_lds((const unsigned*)((const char*)(gbase) + (voff)[_i]), (LAS unsigned*)(lds + (bufoff) + ldsw + _i * 8192), 16, 0, 0); } while (0)
; #define PG8_LDA(dst, b, h) do { _Pragma("unroll") for (int m = 0; m < 4; ++m) _Pragma("unroll") for (int k = 0; k < 2; ++k) dst[m][k] = *(const LAS bf16x8*)(lds + PG8_SA(b, h) + aoff + m * 2048 + k * 1024); } while (0)
; #define PG8_LDB(dst, b, h) do { _Pragma("unroll") for (int n = 0; n < 2; ++n) _Pragma("unroll") for (int k = 0; k < 2; ++k) dst[n][k] = *(const LAS bf16x8*)(lds + PG8_SB(b, h) + boff + n * 2048 + k * 1024); } while (0)
; #define PG8_WAIT_V(n) asm volatile("s_waitcnt vmcnt(" #n ")" ::: "memory")
; #define PG8_BAR __builtin_amdgcn_s_barrier()
; template <class Epi, class Sched = StaticOrder, class EpiSub = NoSub, bool FAST = false>
; __device__ __forceinline__ void gemm_phase(LAS unsigned char* lds, const Gemm g, const Sched& S, const Epi& E, const EpiSub& ES = EpiSub()) {
;     ...
;         const bool has_next = S.next(ui + 1, nxt);
;         const size_t nko = (has_next && nxt.kb >= 0) ? nxt.kb * ksubB : 0;
;         const char* nA = has_next ? (const char*)g.A + (size_t)nxt.pm * tstepA + (size_t)nxt.pn * g.acs + nko : cA; const char* nB = has_next ? (const char*)g.Bt + (size_t)nxt.pn * tstepB + nko : cB;
;         const int nt = cur.kb < 0 ? ntMain : ntSub;
;         for (int t = 0; t < nt; t += 2) {
;             const bool last = (t == nt - 2);
;             const char* a1 = cA + (size_t)(t + 1) * kstep;
;             const char* a2 = last ? nA : cA + (size_t)(t + 2) * kstep; const char* b2 = last ? nB : cB + (size_t)(t + 2) * kstep;
;             const char* a3 = a2 + kstep; const char* b3 = b2 + kstep;
;             if constexpr (FAST && PG8_SP2) {
;             PG8_LDB(B0, 0, 0); PG8_LDB(B1, 0, 1); PG8_SCHED; PG8_LDA(At, 0, 0); PG8_STAGE(PG8_SA(1, 1), a1 + hstepA, voffA);
;             PG8_WAIT_V(8); PG8_WAIT_L(0); PG8_BAR; PG8_MMA(0, 0, At, B0); PG8_MMA(0, 1, At, B1); PG8_BAR; PG8_SCHED;
;             PG8_LDA(At, 0, 1); PG8_STAGE(PG8_SB(0, 0), b2, voffB); PG8_STAGE(PG8_SB(0, 1), b2 + hstepB, voffB); PG8_STAGE(PG8_SA(0, 0), a2, voffA);
;             PG8_WAIT_V(8); PG8_WAIT_L(0); PG8_BAR; PG8_MMA(1, 0, At, B0); PG8_MMA(1, 1, At, B1); PG8_BAR; PG8_SCHED;
.LBB0_216:
	ds_read_b128 v[154:157], v150
	ds_read_b128 v[158:161], v150 offset:1024
	ds_read_b128 v[162:165], v150 offset:2048
	ds_read_b128 v[166:169], v150 offset:3072
	ds_read_b128 v[170:173], v151
	ds_read_b128 v[174:177], v151 offset:1024
	ds_read_b128 v[178:181], v151 offset:2048
	ds_read_b128 v[182:185], v151 offset:3072
	s_add_u32 s24, s22, 0xfff80080
	s_addc_u32 s25, s23, -1
	s_cmp_eq_u32 s50, 28
	s_cselect_b32 s27, s2, s25
	s_cselect_b32 s26, s3, s24
	s_cselect_b32 s25, s13, s49
	s_cselect_b32 s24, s15, s48
	v_lshl_add_u64 v[144:145], s[22:23], 0, v[136:137]
	s_add_i32 m0, s21, 0xc000
	ds_read_b128 v[186:189], v152
	ds_read_b128 v[194:197], v152 offset:1024
	ds_read_b128 v[198:201], v152 offset:2048
	ds_read_b128 v[202:205], v152 offset:3072
	ds_read_b128 v[206:209], v152 offset:4096
	ds_read_b128 v[210:213], v152 offset:5120
	ds_read_b128 v[214:217], v152 offset:6144
	ds_read_b128 v[218:221], v152 offset:7168
	global_load_lds_dwordx4 v[144:145], off
	v_lshl_add_u64 v[144:145], s[22:23], 0, v[138:139]
	s_add_i32 m0, s21, 0xe000
	s_nop 0
	global_load_lds_dwordx4 v[144:145], off
	s_waitcnt vmcnt(8)
	s_waitcnt lgkmcnt(0)
	s_barrier
	s_setprio 1
	v_mfma_f32_16x16x32_bf16 v[124:127], v[154:157], v[186:189], v[124:127]
	v_mfma_f32_16x16x32_bf16 v[120:123], v[162:165], v[186:189], v[120:123]
	v_mfma_f32_16x16x32_bf16 v[116:119], v[154:157], v[198:201], v[116:119]
	v_mfma_f32_16x16x32_bf16 v[108:111], v[162:165], v[198:201], v[108:111]
	v_mfma_f32_16x16x32_bf16 v[100:103], v[154:157], v[206:209], v[100:103]
	v_mfma_f32_16x16x32_bf16 v[92:95], v[162:165], v[206:209], v[92:95]
	v_mfma_f32_16x16x32_bf16 v[84:87], v[154:157], v[214:217], v[84:87]
	v_mfma_f32_16x16x32_bf16 v[76:79], v[162:165], v[214:217], v[76:79]
	v_mfma_f32_16x16x32_bf16 v[124:127], v[158:161], v[194:197], v[124:127]
	v_mfma_f32_16x16x32_bf16 v[120:123], v[166:169], v[194:197], v[120:123]
	v_mfma_f32_16x16x32_bf16 v[116:119], v[158:161], v[202:205], v[116:119]
	v_mfma_f32_16x16x32_bf16 v[108:111], v[166:169], v[202:205], v[108:111]
	v_mfma_f32_16x16x32_bf16 v[100:103], v[158:161], v[210:213], v[100:103]
	v_mfma_f32_16x16x32_bf16 v[92:95], v[166:169], v[210:213], v[92:95]
	v_mfma_f32_16x16x32_bf16 v[84:87], v[158:161], v[218:221], v[84:87]
	v_mfma_f32_16x16x32_bf16 v[76:79], v[166:169], v[218:221], v[76:79]
	v_mfma_f32_16x16x32_bf16 v[112:115], v[170:173], v[186:189], v[112:115]
	v_mfma_f32_16x16x32_bf16 v[104:107], v[178:181], v[186:189], v[104:107]
	v_mfma_f32_16x16x32_bf16 v[96:99], v[170:173], v[198:201], v[96:99]
	v_mfma_f32_16x16x32_bf16 v[88:91], v[178:181], v[198:201], v[88:91]
	v_mfma_f32_16x16x32_bf16 v[80:83], v[170:173], v[206:209], v[80:83]
	v_mfma_f32_16x16x32_bf16 v[72:75], v[178:181], v[206:209], v[72:75]
	v_mfma_f32_16x16x32_bf16 v[68:71], v[170:173], v[214:217], v[68:71]
	v_mfma_f32_16x16x32_bf16 v[64:67], v[178:181], v[214:217], v[64:67]
	v_mfma_f32_16x16x32_bf16 v[112:115], v[174:177], v[194:197], v[112:115]
	v_mfma_f32_16x16x32_bf16 v[104:107], v[182:185], v[194:197], v[104:107]
	v_mfma_f32_16x16x32_bf16 v[96:99], v[174:177], v[202:205], v[96:99]
	v_mfma_f32_16x16x32_bf16 v[88:91], v[182:185], v[202:205], v[88:91]
	v_mfma_f32_16x16x32_bf16 v[80:83], v[174:177], v[210:213], v[80:83]
	v_mfma_f32_16x16x32_bf16 v[72:75], v[182:185], v[210:213], v[72:75]
	v_mfma_f32_16x16x32_bf16 v[68:71], v[174:177], v[218:221], v[68:71]
	v_mfma_f32_16x16x32_bf16 v[64:67], v[182:185], v[218:221], v[64:67]
	s_setprio 0
	s_barrier
	s_add_i32 s51, s41, s30
	v_lshl_add_u64 v[144:145], s[24:25], 0, v[130:131]
	s_mov_b32 m0, s51
	ds_read_b128 v[186:189], v152 offset:16384
	ds_read_b128 v[194:197], v152 offset:17408
	ds_read_b128 v[198:201], v152 offset:18432
	ds_read_b128 v[202:205], v152 offset:19456
	ds_read_b128 v[206:209], v152 offset:20480
	ds_read_b128 v[210:213], v152 offset:21504
	ds_read_b128 v[214:217], v152 offset:22528
	ds_read_b128 v[218:221], v152 offset:23552
	global_load_lds_dwordx4 v[144:145], off
	s_add_i32 m0, s51, 0x2000
	s_add_u32 s68, s24, 0x80000
	v_lshl_add_u64 v[190:191], s[24:25], 0, v[134:135]
	s_addc_u32 s69, s25, 0
	s_add_i32 s51, s42, s30
	global_load_lds_dwordx4 v[190:191], off
	v_lshl_add_u64 v[222:223], s[68:69], 0, v[130:131]
	s_mov_b32 m0, s51
	v_lshl_add_u64 v[224:225], s[26:27], 0, v[132:133]
	global_load_lds_dwordx4 v[222:223], off
	v_lshl_add_u64 v[222:223], s[68:69], 0, v[134:135]
	s_add_i32 m0, s51, 0x2000
	s_nop 0
	global_load_lds_dwordx4 v[222:223], off
	v_lshl_add_u64 v[222:223], s[26:27], 0, v[128:129]
	s_mov_b32 m0, s21
	s_nop 0
	global_load_lds_dwordx4 v[222:223], off
	s_mov_b32 m0, s34
	s_nop 0
	global_load_lds_dwordx4 v[224:225], off
	s_waitcnt vmcnt(8)
	s_waitcnt lgkmcnt(0)
	s_barrier
; #define PG8_STAGE(bufoff, gbase, voff) do { _Pragma("unroll") for (int _i = 0; _i < 2; ++_i) \
;         __builtin_amdgcn_global_load_lds((const unsigned*)((const char*)(gbase) + (voff)[_i]), (LAS unsigned*)(lds + (bufoff) + ldsw + _i * 8192), 16, 0, 0); } while (0)
; #define PG8_LDA(dst, b, h) do { _Pragma("unroll") for (int m = 0; m < 4; ++m) _Pragma("unroll") for (int k = 0; k < 2; ++k) dst[m][k] = *(const LAS bf16x8*)(lds + PG8_SA(b, h) + aoff + m * 2048 + k * 1024); } while (0)
; #define PG8_LDB(dst, b, h) do { _Pragma("unroll") for (int n = 0; n < 2; ++n) _Pragma("unroll") for (int k = 0; k < 2; ++k) dst[n][k] = *(const LAS bf16x8*)(lds + PG8_SB(b, h) + boff + n * 2048 + k * 1024); } while (0)
; #define PG8_MMA(ai, bj, At, Bt) do { __builtin_amdgcn_s_setprio(1); _Pragma("unroll") for (int m = 0; m < 4; ++m) _Pragma("unroll") for (int n = 0; n < 2; ++n) _Pragma("unroll") for (int k = 0; k < 2; ++k) \
;         acc[ai][bj][m][n] = __builtin_amdgcn_mfma_f32_16x16x32_bf16(Bt[n][k], At[m][k], acc[ai][bj][m][n], 0, 0, 0); __builtin_amdgcn_s_setprio(0); } while (0)
; #define PG8_WAIT_V(n) asm volatile("s_waitcnt vmcnt(" #n ")" ::: "memory")
; #define PG8_WAIT_L(n) asm volatile("s_waitcnt lgkmcnt(" #n ")" ::: "memory")
; #define PG8_BAR __builtin_amdgcn_s_barrier()
; #define PG8_SCHED __builtin_amdgcn_sched_barrier(0)
; template <class Epi, class Sched = StaticOrder, class EpiSub = NoSub, bool FAST = false>
; __device__ __forceinline__ void gemm_phase(LAS unsigned char* lds, const Gemm g, const Sched& S, const Epi& E, const EpiSub& ES = EpiSub()) {
;     ...
;             PG8_WAIT_V(8); PG8_WAIT_L(0); PG8_BAR; PG8_MMA(1, 0, At, B0); PG8_MMA(1, 1, At, B1); PG8_BAR; PG8_SCHED;
;             PG8_LDB(B0, 1, 0); PG8_LDB(B1, 1, 1); PG8_SCHED; PG8_LDA(At, 1, 0); PG8_STAGE(PG8_SA(0, 1), a2 + hstepA, voffA);
;             PG8_WAIT_V(8); PG8_WAIT_L(0); PG8_BAR; PG8_MMA(0, 0, At, B0); PG8_MMA(0, 1, At, B1); PG8_BAR; PG8_SCHED;
	s_setprio 1
	v_mfma_f32_16x16x32_bf16 v[60:63], v[154:157], v[186:189], v[60:63]
	v_mfma_f32_16x16x32_bf16 v[56:59], v[162:165], v[186:189], v[56:59]
	v_mfma_f32_16x16x32_bf16 v[52:55], v[154:157], v[198:201], v[52:55]
	v_mfma_f32_16x16x32_bf16 v[44:47], v[162:165], v[198:201], v[44:47]
	v_mfma_f32_16x16x32_bf16 v[36:39], v[154:157], v[206:209], v[36:39]
	v_mfma_f32_16x16x32_bf16 v[28:31], v[162:165], v[206:209], v[28:31]
	v_mfma_f32_16x16x32_bf16 v[20:23], v[154:157], v[214:217], v[20:23]
	v_mfma_f32_16x16x32_bf16 v[12:15], v[162:165], v[214:217], v[12:15]
	v_mfma_f32_16x16x32_bf16 v[60:63], v[158:161], v[194:197], v[60:63]
	v_mfma_f32_16x16x32_bf16 v[56:59], v[166:169], v[194:197], v[56:59]
	v_mfma_f32_16x16x32_bf16 v[52:55], v[158:161], v[202:205], v[52:55]
	v_mfma_f32_16x16x32_bf16 v[44:47], v[166:169], v[202:205], v[44:47]
	v_mfma_f32_16x16x32_bf16 v[36:39], v[158:161], v[210:213], v[36:39]
	v_mfma_f32_16x16x32_bf16 v[28:31], v[166:169], v[210:213], v[28:31]
	v_mfma_f32_16x16x32_bf16 v[20:23], v[158:161], v[218:221], v[20:23]
	v_mfma_f32_16x16x32_bf16 v[12:15], v[166:169], v[218:221], v[12:15]
	v_mfma_f32_16x16x32_bf16 v[48:51], v[170:173], v[186:189], v[48:51]
	v_mfma_f32_16x16x32_bf16 v[40:43], v[178:181], v[186:189], v[40:43]
	v_mfma_f32_16x16x32_bf16 v[32:35], v[170:173], v[198:201], v[32:35]
	v_mfma_f32_16x16x32_bf16 v[24:27], v[178:181], v[198:201], v[24:27]
	v_mfma_f32_16x16x32_bf16 v[16:19], v[170:173], v[206:209], v[16:19]
	v_mfma_f32_16x16x32_bf16 v[8:11], v[178:181], v[206:209], v[8:11]
	v_mfma_f32_16x16x32_bf16 v[4:7], v[170:173], v[214:217], v[4:7]
	v_mfma_f32_16x16x32_bf16 v[0:3], v[178:181], v[214:217], v[0:3]
	v_mfma_f32_16x16x32_bf16 v[48:51], v[174:177], v[194:197], v[48:51]
	v_mfma_f32_16x16x32_bf16 v[40:43], v[182:185], v[194:197], v[40:43]
	v_mfma_f32_16x16x32_bf16 v[32:35], v[174:177], v[202:205], v[32:35]
	v_mfma_f32_16x16x32_bf16 v[24:27], v[182:185], v[202:205], v[24:27]
	v_mfma_f32_16x16x32_bf16 v[16:19], v[174:177], v[210:213], v[16:19]
	v_mfma_f32_16x16x32_bf16 v[8:11], v[182:185], v[210:213], v[8:11]
	v_mfma_f32_16x16x32_bf16 v[4:7], v[174:177], v[218:221], v[4:7]
	v_mfma_f32_16x16x32_bf16 v[0:3], v[182:185], v[218:221], v[0:3]
	s_setprio 0
	s_barrier
	s_add_i32 s51, 0, 0x18000
	v_add_u32_e32 v153, s51, v148
	s_add_i32 s68, 0, 0x1c000
	ds_read_b128 v[154:157], v153
	ds_read_b128 v[158:161], v153 offset:1024
	ds_read_b128 v[162:165], v153 offset:2048
	ds_read_b128 v[166:169], v153 offset:3072
	v_add_u32_e32 v153, s68, v148
	ds_read_b128 v[170:173], v153
	ds_read_b128 v[174:177], v153 offset:1024
	ds_read_b128 v[178:181], v153 offset:2048
	ds_read_b128 v[182:185], v153 offset:3072
	s_add_u32 s26, s26, 0x80000
	s_addc_u32 s27, s27, 0
	s_mov_b32 m0, s35
	v_lshl_add_u64 v[226:227], s[26:27], 0, v[128:129]
	ds_read_b128 v[186:189], v152 offset:32768
	ds_read_b128 v[194:197], v152 offset:33792
	ds_read_b128 v[198:201], v152 offset:34816
	ds_read_b128 v[202:205], v152 offset:35840
	ds_read_b128 v[206:209], v152 offset:36864
	ds_read_b128 v[210:213], v152 offset:37888
	ds_read_b128 v[214:217], v152 offset:38912
	ds_read_b128 v[218:221], v152 offset:39936
	global_load_lds_dwordx4 v[226:227], off
	v_lshl_add_u64 v[226:227], s[26:27], 0, v[132:133]
	s_mov_b32 m0, s36
	s_nop 0
	global_load_lds_dwordx4 v[226:227], off
	s_waitcnt vmcnt(8)
	s_waitcnt lgkmcnt(0)
	s_barrier
	s_setprio 1
	v_mfma_f32_16x16x32_bf16 v[124:127], v[154:157], v[186:189], v[124:127]
	v_mfma_f32_16x16x32_bf16 v[120:123], v[162:165], v[186:189], v[120:123]
	v_mfma_f32_16x16x32_bf16 v[116:119], v[154:157], v[198:201], v[116:119]
	v_mfma_f32_16x16x32_bf16 v[108:111], v[162:165], v[198:201], v[108:111]
	v_mfma_f32_16x16x32_bf16 v[100:103], v[154:157], v[206:209], v[100:103]
	v_mfma_f32_16x16x32_bf16 v[92:95], v[162:165], v[206:209], v[92:95]
	v_mfma_f32_16x16x32_bf16 v[84:87], v[154:157], v[214:217], v[84:87]
	v_mfma_f32_16x16x32_bf16 v[76:79], v[162:165], v[214:217], v[76:79]
	v_mfma_f32_16x16x32_bf16 v[124:127], v[158:161], v[194:197], v[124:127]
	v_mfma_f32_16x16x32_bf16 v[120:123], v[166:169], v[194:197], v[120:123]
	v_mfma_f32_16x16x32_bf16 v[116:119], v[158:161], v[202:205], v[116:119]
	v_mfma_f32_16x16x32_bf16 v[108:111], v[166:169], v[202:205], v[108:111]
	v_mfma_f32_16x16x32_bf16 v[100:103], v[158:161], v[210:213], v[100:103]
	v_mfma_f32_16x16x32_bf16 v[92:95], v[166:169], v[210:213], v[92:95]
	v_mfma_f32_16x16x32_bf16 v[84:87], v[158:161], v[218:221], v[84:87]
	v_mfma_f32_16x16x32_bf16 v[76:79], v[166:169], v[218:221], v[76:79]
	v_mfma_f32_16x16x32_bf16 v[112:115], v[170:173], v[186:189], v[112:115]
	v_mfma_f32_16x16x32_bf16 v[104:107], v[178:181], v[186:189], v[104:107]
	v_mfma_f32_16x16x32_bf16 v[96:99], v[170:173], v[198:201], v[96:99]
	v_mfma_f32_16x16x32_bf16 v[88:91], v[178:181], v[198:201], v[88:91]
	v_mfma_f32_16x16x32_bf16 v[80:83], v[170:173], v[206:209], v[80:83]
	v_mfma_f32_16x16x32_bf16 v[72:75], v[178:181], v[206:209], v[72:75]
	v_mfma_f32_16x16x32_bf16 v[68:71], v[170:173], v[214:217], v[68:71]
	v_mfma_f32_16x16x32_bf16 v[64:67], v[178:181], v[214:217], v[64:67]
	v_mfma_f32_16x16x32_bf16 v[112:115], v[174:177], v[194:197], v[112:115]
	v_mfma_f32_16x16x32_bf16 v[104:107], v[182:185], v[194:197], v[104:107]
	v_mfma_f32_16x16x32_bf16 v[96:99], v[174:177], v[202:205], v[96:99]
	v_mfma_f32_16x16x32_bf16 v[88:91], v[182:185], v[202:205], v[88:91]
	v_mfma_f32_16x16x32_bf16 v[80:83], v[174:177], v[210:213], v[80:83]
	v_mfma_f32_16x16x32_bf16 v[72:75], v[182:185], v[210:213], v[72:75]
	v_mfma_f32_16x16x32_bf16 v[68:71], v[174:177], v[218:221], v[68:71]
	v_mfma_f32_16x16x32_bf16 v[64:67], v[182:185], v[218:221], v[64:67]
	s_setprio 0
	s_barrier
; #define PG8_STAGE(bufoff, gbase, voff) do { _Pragma("unroll") for (int _i = 0; _i < 2; ++_i) \
;         __builtin_amdgcn_global_load_lds((const unsigned*)((const char*)(gbase) + (voff)[_i]), (LAS unsigned*)(lds + (bufoff) + ldsw + _i * 8192), 16, 0, 0); } while (0)
; #define PG8_LDA(dst, b, h) do { _Pragma("unroll") for (int m = 0; m < 4; ++m) _Pragma("unroll") for (int k = 0; k < 2; ++k) dst[m][k] = *(const LAS bf16x8*)(lds + PG8_SA(b, h) + aoff + m * 2048 + k * 1024); } while (0)
; #define PG8_MMA(ai, bj, At, Bt) do { __builtin_amdgcn_s_setprio(1); _Pragma("unroll") for (int m = 0; m < 4; ++m) _Pragma("unroll") for (int n = 0; n < 2; ++n) _Pragma("unroll") for (int k = 0; k < 2; ++k) \
;         acc[ai][bj][m][n] = __builtin_amdgcn_mfma_f32_16x16x32_bf16(Bt[n][k], At[m][k], acc[ai][bj][m][n], 0, 0, 0); __builtin_amdgcn_s_setprio(0); } while (0)
; #define PG8_WAIT_V(n) asm volatile("s_waitcnt vmcnt(" #n ")" ::: "memory")
; #define PG8_WAIT_L(n) asm volatile("s_waitcnt lgkmcnt(" #n ")" ::: "memory")
; #define PG8_BAR __builtin_amdgcn_s_barrier()
; #define PG8_SCHED __builtin_amdgcn_sched_barrier(0)
; template <class Epi, class Sched = StaticOrder, class EpiSub = NoSub, bool FAST = false>
; __device__ __forceinline__ void gemm_phase(LAS unsigned char* lds, const Gemm g, const Sched& S, const Epi& E, const EpiSub& ES = EpiSub()) {
;     ...
;             PG8_LDA(At, 1, 1); PG8_STAGE(PG8_SB(1, 0), b3, voffB); PG8_STAGE(PG8_SB(1, 1), b3 + hstepB, voffB); PG8_STAGE(PG8_SA(1, 0), a3, voffA);
;             PG8_WAIT_V(8); PG8_WAIT_L(0); PG8_BAR; PG8_MMA(1, 0, At, B0); PG8_MMA(1, 1, At, B1); PG8_BAR; PG8_SCHED;
;     ...
;         if constexpr (FAST && PG8_ALIGN) { if (wr == 0) PG8_BAR; }
	s_add_i32 s26, s51, s30
	v_lshl_add_u64 v[144:145], v[144:145], 0, s[8:9]
	s_mov_b32 m0, s26
	ds_read_b128 v[186:189], v152 offset:49152
	ds_read_b128 v[194:197], v152 offset:50176
	ds_read_b128 v[198:201], v152 offset:51200
	ds_read_b128 v[202:205], v152 offset:52224
	ds_read_b128 v[206:209], v152 offset:53248
	ds_read_b128 v[210:213], v152 offset:54272
	ds_read_b128 v[214:217], v152 offset:55296
	ds_read_b128 v[218:221], v152 offset:56320
	global_load_lds_dwordx4 v[144:145], off
	s_add_i32 m0, s26, 0x2000
	s_add_u32 s24, s24, 0x80080
	v_lshl_add_u64 v[144:145], v[190:191], 0, s[8:9]
	s_addc_u32 s25, s25, 0
	s_add_i32 s26, s68, s30
	global_load_lds_dwordx4 v[144:145], off
	v_lshl_add_u64 v[144:145], s[24:25], 0, v[130:131]
	s_mov_b32 m0, s26
	s_nop 0
	global_load_lds_dwordx4 v[144:145], off
	v_lshl_add_u64 v[144:145], s[24:25], 0, v[134:135]
	s_add_i32 m0, s26, 0x2000
	s_nop 0
	global_load_lds_dwordx4 v[144:145], off
	v_lshl_add_u64 v[144:145], v[222:223], 0, s[8:9]
	s_mov_b32 m0, s39
	s_nop 0
	global_load_lds_dwordx4 v[144:145], off
	v_lshl_add_u64 v[144:145], v[224:225], 0, s[8:9]
	s_mov_b32 m0, s40
	s_nop 0
	global_load_lds_dwordx4 v[144:145], off
	s_waitcnt vmcnt(8)
	s_waitcnt lgkmcnt(0)
	s_barrier
	s_setprio 1
	v_mfma_f32_16x16x32_bf16 v[60:63], v[154:157], v[186:189], v[60:63]
	v_mfma_f32_16x16x32_bf16 v[56:59], v[162:165], v[186:189], v[56:59]
	v_mfma_f32_16x16x32_bf16 v[52:55], v[154:157], v[198:201], v[52:55]
	v_mfma_f32_16x16x32_bf16 v[44:47], v[162:165], v[198:201], v[44:47]
	v_mfma_f32_16x16x32_bf16 v[36:39], v[154:157], v[206:209], v[36:39]
	v_mfma_f32_16x16x32_bf16 v[28:31], v[162:165], v[206:209], v[28:31]
	v_mfma_f32_16x16x32_bf16 v[20:23], v[154:157], v[214:217], v[20:23]
	v_mfma_f32_16x16x32_bf16 v[12:15], v[162:165], v[214:217], v[12:15]
	v_mfma_f32_16x16x32_bf16 v[60:63], v[158:161], v[194:197], v[60:63]
	v_mfma_f32_16x16x32_bf16 v[56:59], v[166:169], v[194:197], v[56:59]
	v_mfma_f32_16x16x32_bf16 v[52:55], v[158:161], v[202:205], v[52:55]
	v_mfma_f32_16x16x32_bf16 v[44:47], v[166:169], v[202:205], v[44:47]
	v_mfma_f32_16x16x32_bf16 v[36:39], v[158:161], v[210:213], v[36:39]
	v_mfma_f32_16x16x32_bf16 v[28:31], v[166:169], v[210:213], v[28:31]
	v_mfma_f32_16x16x32_bf16 v[20:23], v[158:161], v[218:221], v[20:23]
	v_mfma_f32_16x16x32_bf16 v[12:15], v[166:169], v[218:221], v[12:15]
	v_mfma_f32_16x16x32_bf16 v[48:51], v[170:173], v[186:189], v[48:51]
	v_mfma_f32_16x16x32_bf16 v[40:43], v[178:181], v[186:189], v[40:43]
	v_mfma_f32_16x16x32_bf16 v[32:35], v[170:173], v[198:201], v[32:35]
	v_mfma_f32_16x16x32_bf16 v[24:27], v[178:181], v[198:201], v[24:27]
	v_mfma_f32_16x16x32_bf16 v[16:19], v[170:173], v[206:209], v[16:19]
	v_mfma_f32_16x16x32_bf16 v[8:11], v[178:181], v[206:209], v[8:11]
	v_mfma_f32_16x16x32_bf16 v[4:7], v[170:173], v[214:217], v[4:7]
	v_mfma_f32_16x16x32_bf16 v[0:3], v[178:181], v[214:217], v[0:3]
	v_mfma_f32_16x16x32_bf16 v[48:51], v[174:177], v[194:197], v[48:51]
	v_mfma_f32_16x16x32_bf16 v[40:43], v[182:185], v[194:197], v[40:43]
	v_mfma_f32_16x16x32_bf16 v[32:35], v[174:177], v[202:205], v[32:35]
	v_mfma_f32_16x16x32_bf16 v[24:27], v[182:185], v[202:205], v[24:27]
	v_mfma_f32_16x16x32_bf16 v[16:19], v[174:177], v[210:213], v[16:19]
	v_mfma_f32_16x16x32_bf16 v[8:11], v[182:185], v[210:213], v[8:11]
	v_mfma_f32_16x16x32_bf16 v[4:7], v[174:177], v[218:221], v[4:7]
	v_mfma_f32_16x16x32_bf16 v[0:3], v[182:185], v[218:221], v[0:3]
	s_setprio 0
	s_barrier
	s_add_i32 s50, s50, 2
	s_add_u32 s22, s22, 0x100
	s_addc_u32 s23, s23, 0
	s_add_u32 s48, s48, 0x100
	s_addc_u32 s49, s49, 0
	s_cmp_gt_u32 s50, 29
	s_cbranch_scc0 .LBB0_216
	s_and_b64 vcc, exec, s[10:11]
	s_cbranch_vccz .LBB0_219
	s_barrier

; #define PG8_STAGE(bufoff, gbase, voff) do { _Pragma("unroll") for (int _i = 0; _i < 2; ++_i) \
;         __builtin_amdgcn_global_load_lds((const unsigned*)((const char*)(gbase) + (voff)[_i]), (LAS unsigned*)(lds + (bufoff) + ldsw + _i * 8192), 16, 0, 0); } while (0)
; #define PG8_LDA(dst, b, h) do { _Pragma("unroll") for (int m = 0; m < 4; ++m) _Pragma("unroll") for (int k = 0; k < 2; ++k) dst[m][k] = *(const LAS bf16x8*)(lds + PG8_SA(b, h) + aoff + m * 2048 + k * 1024); } while (0)
; #define PG8_LDB(dst, b, h) do { _Pragma("unroll") for (int n = 0; n < 2; ++n) _Pragma("unroll") for (int k = 0; k < 2; ++k) dst[n][k] = *(const LAS bf16x8*)(lds + PG8_SB(b, h) + boff + n * 2048 + k * 1024); } while (0)
; #define PG8_WAIT_V(n) asm volatile("s_waitcnt vmcnt(" #n ")" ::: "memory")
; #define PG8_BAR __builtin_amdgcn_s_barrier()
; template <class Epi, class Sched = StaticOrder, class EpiSub = NoSub, bool FAST = false>
; __device__ __forceinline__ void gemm_phase(LAS unsigned char* lds, const Gemm g, const Sched& S, const Epi& E, const EpiSub& ES = EpiSub()) {
;     ...
;         const bool has_next = S.next(ui + 1, nxt);
;         const size_t nko = (has_next && nxt.kb >= 0) ? nxt.kb * ksubB : 0;
;         const char* nA = has_next ? (const char*)g.A + (size_t)nxt.pm * tstepA + (size_t)nxt.pn * g.acs + nko : cA; const char* nB = has_next ? (const char*)g.Bt + (size_t)nxt.pn * tstepB + nko : cB;
;         const int nt = cur.kb < 0 ? ntMain : ntSub;
;         for (int t = 0; t < nt; t += 2) {
;             const bool last = (t == nt - 2);
;             const char* a1 = cA + (size_t)(t + 1) * kstep;
;             const char* a2 = last ? nA : cA + (size_t)(t + 2) * kstep; const char* b2 = last ? nB : cB + (size_t)(t + 2) * kstep;
;             const char* a3 = a2 + kstep; const char* b3 = b2 + kstep;
;             if constexpr (FAST && PG8_SP2) {
;             PG8_LDB(B0, 0, 0); PG8_LDB(B1, 0, 1); PG8_SCHED; PG8_LDA(At, 0, 0); PG8_STAGE(PG8_SA(1, 1), a1 + hstepA, voffA);
;             PG8_WAIT_V(8); PG8_WAIT_L(0); PG8_BAR; PG8_MMA(0, 0, At, B0); PG8_MMA(0, 1, At, B1); PG8_BAR; PG8_SCHED;
;             PG8_LDA(At, 0, 1); PG8_STAGE(PG8_SB(0, 0), b2, voffB); PG8_STAGE(PG8_SB(0, 1), b2 + hstepB, voffB); PG8_STAGE(PG8_SA(0, 0), a2, voffA);
;             PG8_WAIT_V(8); PG8_WAIT_L(0); PG8_BAR; PG8_MMA(1, 0, At, B0); PG8_MMA(1, 1, At, B1); PG8_BAR; PG8_SCHED;
.LBB0_600:
	ds_read_b128 v[100:103], v186
	ds_read_b128 v[112:115], v186 offset:1024
	ds_read_b128 v[124:127], v186 offset:2048
	ds_read_b128 v[136:139], v186 offset:3072
	ds_read_b128 v[144:147], v187
	ds_read_b128 v[148:151], v187 offset:1024
	ds_read_b128 v[152:155], v187 offset:2048
	ds_read_b128 v[170:173], v187 offset:3072
	s_add_i32 s51, s50, 2
	s_add_u32 s42, s40, 0xfffc0080
	s_addc_u32 s43, s41, -1
	s_cmp_eq_u32 s33, s50
	s_cselect_b32 s53, s1, s43
	s_cselect_b32 s52, s5, s42
	s_cselect_b32 s43, s7, s49
	s_cselect_b32 s42, s25, s48
	v_lshl_add_u64 v[190:191], s[40:41], 0, v[164:165]
	s_add_i32 m0, s55, 0xc000
	ds_read_b128 v[174:177], v188
	ds_read_b128 v[178:181], v188 offset:1024
	ds_read_b128 v[194:197], v188 offset:2048
	ds_read_b128 v[198:201], v188 offset:3072
	ds_read_b128 v[202:205], v188 offset:4096
	ds_read_b128 v[206:209], v188 offset:5120
	ds_read_b128 v[210:213], v188 offset:6144
	ds_read_b128 v[214:217], v188 offset:7168
	global_load_lds_dwordx4 v[190:191], off
	v_lshl_add_u64 v[190:191], s[40:41], 0, v[166:167]
	s_add_i32 m0, s55, 0xe000
	s_nop 0
	global_load_lds_dwordx4 v[190:191], off
	s_waitcnt vmcnt(8)
	s_waitcnt lgkmcnt(0)
	s_barrier
	s_setprio 1
	v_mfma_f32_16x16x32_bf16 v[140:143], v[100:103], v[174:177], v[140:143]
	v_mfma_f32_16x16x32_bf16 v[132:135], v[124:127], v[174:177], v[132:135]
	v_mfma_f32_16x16x32_bf16 v[116:119], v[100:103], v[194:197], v[116:119]
	v_mfma_f32_16x16x32_bf16 v[108:111], v[124:127], v[194:197], v[108:111]
	v_mfma_f32_16x16x32_bf16 v[92:95], v[100:103], v[202:205], v[92:95]
	v_mfma_f32_16x16x32_bf16 v[88:91], v[124:127], v[202:205], v[88:91]
	v_mfma_f32_16x16x32_bf16 v[76:79], v[100:103], v[210:213], v[76:79]
	v_mfma_f32_16x16x32_bf16 v[72:75], v[124:127], v[210:213], v[72:75]
	v_mfma_f32_16x16x32_bf16 v[140:143], v[112:115], v[178:181], v[140:143]
	v_mfma_f32_16x16x32_bf16 v[132:135], v[136:139], v[178:181], v[132:135]
	v_mfma_f32_16x16x32_bf16 v[116:119], v[112:115], v[198:201], v[116:119]
	v_mfma_f32_16x16x32_bf16 v[108:111], v[136:139], v[198:201], v[108:111]
	v_mfma_f32_16x16x32_bf16 v[92:95], v[112:115], v[206:209], v[92:95]
	v_mfma_f32_16x16x32_bf16 v[88:91], v[136:139], v[206:209], v[88:91]
	v_mfma_f32_16x16x32_bf16 v[76:79], v[112:115], v[214:217], v[76:79]
	v_mfma_f32_16x16x32_bf16 v[72:75], v[136:139], v[214:217], v[72:75]
	v_mfma_f32_16x16x32_bf16 v[128:131], v[144:147], v[174:177], v[128:131]
	v_mfma_f32_16x16x32_bf16 v[120:123], v[152:155], v[174:177], v[120:123]
	v_mfma_f32_16x16x32_bf16 v[104:107], v[144:147], v[194:197], v[104:107]
	v_mfma_f32_16x16x32_bf16 v[96:99], v[152:155], v[194:197], v[96:99]
	v_mfma_f32_16x16x32_bf16 v[84:87], v[144:147], v[202:205], v[84:87]
	v_mfma_f32_16x16x32_bf16 v[80:83], v[152:155], v[202:205], v[80:83]
	v_mfma_f32_16x16x32_bf16 v[68:71], v[144:147], v[210:213], v[68:71]
	v_mfma_f32_16x16x32_bf16 v[64:67], v[152:155], v[210:213], v[64:67]
	v_mfma_f32_16x16x32_bf16 v[128:131], v[148:151], v[178:181], v[128:131]
	v_mfma_f32_16x16x32_bf16 v[120:123], v[170:173], v[178:181], v[120:123]
	v_mfma_f32_16x16x32_bf16 v[104:107], v[148:151], v[198:201], v[104:107]
	v_mfma_f32_16x16x32_bf16 v[96:99], v[170:173], v[198:201], v[96:99]
	v_mfma_f32_16x16x32_bf16 v[84:87], v[148:151], v[206:209], v[84:87]
	v_mfma_f32_16x16x32_bf16 v[80:83], v[170:173], v[206:209], v[80:83]
	v_mfma_f32_16x16x32_bf16 v[68:71], v[148:151], v[214:217], v[68:71]
	v_mfma_f32_16x16x32_bf16 v[64:67], v[170:173], v[214:217], v[64:67]
	s_setprio 0
	s_barrier
	s_add_i32 s50, s75, s54
	v_lshl_add_u64 v[190:191], s[42:43], 0, v[158:159]
	s_mov_b32 m0, s50
	ds_read_b128 v[174:177], v188 offset:16384
	ds_read_b128 v[178:181], v188 offset:17408
	ds_read_b128 v[194:197], v188 offset:18432
	ds_read_b128 v[198:201], v188 offset:19456
	ds_read_b128 v[202:205], v188 offset:20480
	ds_read_b128 v[206:209], v188 offset:21504
	ds_read_b128 v[210:213], v188 offset:22528
	ds_read_b128 v[214:217], v188 offset:23552
	global_load_lds_dwordx4 v[190:191], off
	s_add_i32 m0, s50, 0x2000
	s_add_u32 s70, s42, 0x40000
	v_lshl_add_u64 v[218:219], s[42:43], 0, v[162:163]
	s_addc_u32 s71, s43, 0
	s_add_i32 s50, s80, s54
	global_load_lds_dwordx4 v[218:219], off
	v_lshl_add_u64 v[220:221], s[70:71], 0, v[158:159]
	s_mov_b32 m0, s50
	v_lshl_add_u64 v[222:223], s[52:53], 0, v[160:161]
	global_load_lds_dwordx4 v[220:221], off
	v_lshl_add_u64 v[220:221], s[70:71], 0, v[162:163]
	s_add_i32 m0, s50, 0x2000
	s_nop 0
	global_load_lds_dwordx4 v[220:221], off
	v_lshl_add_u64 v[220:221], s[52:53], 0, v[156:157]
	s_mov_b32 m0, s55
	s_nop 0
	global_load_lds_dwordx4 v[220:221], off
	s_mov_b32 m0, s56
	s_nop 0
	global_load_lds_dwordx4 v[222:223], off
	s_waitcnt vmcnt(8)
	s_waitcnt lgkmcnt(0)
	s_barrier
; #define PG8_STAGE(bufoff, gbase, voff) do { _Pragma("unroll") for (int _i = 0; _i < 2; ++_i) \
;         __builtin_amdgcn_global_load_lds((const unsigned*)((const char*)(gbase) + (voff)[_i]), (LAS unsigned*)(lds + (bufoff) + ldsw + _i * 8192), 16, 0, 0); } while (0)
; #define PG8_LDA(dst, b, h) do { _Pragma("unroll") for (int m = 0; m < 4; ++m) _Pragma("unroll") for (int k = 0; k < 2; ++k) dst[m][k] = *(const LAS bf16x8*)(lds + PG8_SA(b, h) + aoff + m * 2048 + k * 1024); } while (0)
; #define PG8_LDB(dst, b, h) do { _Pragma("unroll") for (int n = 0; n < 2; ++n) _Pragma("unroll") for (int k = 0; k < 2; ++k) dst[n][k] = *(const LAS bf16x8*)(lds + PG8_SB(b, h) + boff + n * 2048 + k * 1024); } while (0)
; #define PG8_MMA(ai, bj, At, Bt) do { __builtin_amdgcn_s_setprio(1); _Pragma("unroll") for (int m = 0; m < 4; ++m) _Pragma("unroll") for (int n = 0; n < 2; ++n) _Pragma("unroll") for (int k = 0; k < 2; ++k) \
;         acc[ai][bj][m][n] = __builtin_amdgcn_mfma_f32_16x16x32_bf16(Bt[n][k], At[m][k], acc[ai][bj][m][n], 0, 0, 0); __builtin_amdgcn_s_setprio(0); } while (0)
; #define PG8_WAIT_V(n) asm volatile("s_waitcnt vmcnt(" #n ")" ::: "memory")
; #define PG8_WAIT_L(n) asm volatile("s_waitcnt lgkmcnt(" #n ")" ::: "memory")
; #define PG8_BAR __builtin_amdgcn_s_barrier()
; #define PG8_SCHED __builtin_amdgcn_sched_barrier(0)
; template <class Epi, class Sched = StaticOrder, class EpiSub = NoSub, bool FAST = false>
; __device__ __forceinline__ void gemm_phase(LAS unsigned char* lds, const Gemm g, const Sched& S, const Epi& E, const EpiSub& ES = EpiSub()) {
;     ...
;             PG8_WAIT_V(8); PG8_WAIT_L(0); PG8_BAR; PG8_MMA(1, 0, At, B0); PG8_MMA(1, 1, At, B1); PG8_BAR; PG8_SCHED;
;             PG8_LDB(B0, 1, 0); PG8_LDB(B1, 1, 1); PG8_SCHED; PG8_LDA(At, 1, 0); PG8_STAGE(PG8_SA(0, 1), a2 + hstepA, voffA);
;             PG8_WAIT_V(8); PG8_WAIT_L(0); PG8_BAR; PG8_MMA(0, 0, At, B0); PG8_MMA(0, 1, At, B1); PG8_BAR; PG8_SCHED;
	s_setprio 1
	v_mfma_f32_16x16x32_bf16 v[60:63], v[100:103], v[174:177], v[60:63]
	v_mfma_f32_16x16x32_bf16 v[56:59], v[124:127], v[174:177], v[56:59]
	v_mfma_f32_16x16x32_bf16 v[44:47], v[100:103], v[194:197], v[44:47]
	v_mfma_f32_16x16x32_bf16 v[40:43], v[124:127], v[194:197], v[40:43]
	v_mfma_f32_16x16x32_bf16 v[28:31], v[100:103], v[202:205], v[28:31]
	v_mfma_f32_16x16x32_bf16 v[24:27], v[124:127], v[202:205], v[24:27]
	v_mfma_f32_16x16x32_bf16 v[12:15], v[100:103], v[210:213], v[12:15]
	v_mfma_f32_16x16x32_bf16 v[8:11], v[124:127], v[210:213], v[8:11]
	v_mfma_f32_16x16x32_bf16 v[60:63], v[112:115], v[178:181], v[60:63]
	v_mfma_f32_16x16x32_bf16 v[56:59], v[136:139], v[178:181], v[56:59]
	v_mfma_f32_16x16x32_bf16 v[44:47], v[112:115], v[198:201], v[44:47]
	v_mfma_f32_16x16x32_bf16 v[40:43], v[136:139], v[198:201], v[40:43]
	v_mfma_f32_16x16x32_bf16 v[28:31], v[112:115], v[206:209], v[28:31]
	v_mfma_f32_16x16x32_bf16 v[24:27], v[136:139], v[206:209], v[24:27]
	v_mfma_f32_16x16x32_bf16 v[12:15], v[112:115], v[214:217], v[12:15]
	v_mfma_f32_16x16x32_bf16 v[8:11], v[136:139], v[214:217], v[8:11]
	v_mfma_f32_16x16x32_bf16 v[52:55], v[144:147], v[174:177], v[52:55]
	v_mfma_f32_16x16x32_bf16 v[48:51], v[152:155], v[174:177], v[48:51]
	v_mfma_f32_16x16x32_bf16 v[36:39], v[144:147], v[194:197], v[36:39]
	v_mfma_f32_16x16x32_bf16 v[32:35], v[152:155], v[194:197], v[32:35]
	v_mfma_f32_16x16x32_bf16 v[20:23], v[144:147], v[202:205], v[20:23]
	v_mfma_f32_16x16x32_bf16 v[16:19], v[152:155], v[202:205], v[16:19]
	v_mfma_f32_16x16x32_bf16 v[4:7], v[144:147], v[210:213], v[4:7]
	v_mfma_f32_16x16x32_bf16 v[0:3], v[152:155], v[210:213], v[0:3]
	v_mfma_f32_16x16x32_bf16 v[52:55], v[148:151], v[178:181], v[52:55]
	v_mfma_f32_16x16x32_bf16 v[48:51], v[170:173], v[178:181], v[48:51]
	v_mfma_f32_16x16x32_bf16 v[36:39], v[148:151], v[198:201], v[36:39]
	v_mfma_f32_16x16x32_bf16 v[32:35], v[170:173], v[198:201], v[32:35]
	v_mfma_f32_16x16x32_bf16 v[20:23], v[148:151], v[206:209], v[20:23]
	v_mfma_f32_16x16x32_bf16 v[16:19], v[170:173], v[206:209], v[16:19]
	v_mfma_f32_16x16x32_bf16 v[4:7], v[148:151], v[214:217], v[4:7]
	v_mfma_f32_16x16x32_bf16 v[0:3], v[170:173], v[214:217], v[0:3]
	s_setprio 0
	s_barrier
	s_add_i32 s50, 0, 0x18000
	s_add_i32 s70, 0, 0x1c000
	v_add_u32_e32 v136, s50, v183
	v_add_u32_e32 v170, s70, v183
	ds_read_b128 v[100:103], v136
	ds_read_b128 v[112:115], v136 offset:1024
	ds_read_b128 v[124:127], v136 offset:2048
	ds_read_b128 v[136:139], v136 offset:3072
	ds_read_b128 v[144:147], v170
	ds_read_b128 v[148:151], v170 offset:1024
	ds_read_b128 v[152:155], v170 offset:2048
	ds_read_b128 v[170:173], v170 offset:3072
	s_add_u32 s52, s52, 0x40000
	s_addc_u32 s53, s53, 0
	s_mov_b32 m0, s57
	v_lshl_add_u64 v[224:225], s[52:53], 0, v[156:157]
	ds_read_b128 v[174:177], v188 offset:32768
	ds_read_b128 v[178:181], v188 offset:33792
	ds_read_b128 v[194:197], v188 offset:34816
	ds_read_b128 v[198:201], v188 offset:35840
	ds_read_b128 v[202:205], v188 offset:36864
	ds_read_b128 v[206:209], v188 offset:37888
	ds_read_b128 v[210:213], v188 offset:38912
	ds_read_b128 v[214:217], v188 offset:39936
	global_load_lds_dwordx4 v[224:225], off
	v_lshl_add_u64 v[224:225], s[52:53], 0, v[160:161]
	s_mov_b32 m0, s58
	s_nop 0
	global_load_lds_dwordx4 v[224:225], off
	s_waitcnt vmcnt(8)
	s_waitcnt lgkmcnt(0)
	s_barrier
	s_setprio 1
	v_mfma_f32_16x16x32_bf16 v[140:143], v[100:103], v[174:177], v[140:143]
	v_mfma_f32_16x16x32_bf16 v[132:135], v[124:127], v[174:177], v[132:135]
	v_mfma_f32_16x16x32_bf16 v[116:119], v[100:103], v[194:197], v[116:119]
	v_mfma_f32_16x16x32_bf16 v[108:111], v[124:127], v[194:197], v[108:111]
	v_mfma_f32_16x16x32_bf16 v[92:95], v[100:103], v[202:205], v[92:95]
	v_mfma_f32_16x16x32_bf16 v[88:91], v[124:127], v[202:205], v[88:91]
	v_mfma_f32_16x16x32_bf16 v[76:79], v[100:103], v[210:213], v[76:79]
	v_mfma_f32_16x16x32_bf16 v[72:75], v[124:127], v[210:213], v[72:75]
	v_mfma_f32_16x16x32_bf16 v[140:143], v[112:115], v[178:181], v[140:143]
	v_mfma_f32_16x16x32_bf16 v[132:135], v[136:139], v[178:181], v[132:135]
	v_mfma_f32_16x16x32_bf16 v[116:119], v[112:115], v[198:201], v[116:119]
	v_mfma_f32_16x16x32_bf16 v[108:111], v[136:139], v[198:201], v[108:111]
	v_mfma_f32_16x16x32_bf16 v[92:95], v[112:115], v[206:209], v[92:95]
	v_mfma_f32_16x16x32_bf16 v[88:91], v[136:139], v[206:209], v[88:91]
	v_mfma_f32_16x16x32_bf16 v[76:79], v[112:115], v[214:217], v[76:79]
	v_mfma_f32_16x16x32_bf16 v[72:75], v[136:139], v[214:217], v[72:75]
	v_mfma_f32_16x16x32_bf16 v[128:131], v[144:147], v[174:177], v[128:131]
	v_mfma_f32_16x16x32_bf16 v[120:123], v[152:155], v[174:177], v[120:123]
	v_mfma_f32_16x16x32_bf16 v[104:107], v[144:147], v[194:197], v[104:107]
	v_mfma_f32_16x16x32_bf16 v[96:99], v[152:155], v[194:197], v[96:99]
	v_mfma_f32_16x16x32_bf16 v[84:87], v[144:147], v[202:205], v[84:87]
	v_mfma_f32_16x16x32_bf16 v[80:83], v[152:155], v[202:205], v[80:83]
	v_mfma_f32_16x16x32_bf16 v[68:71], v[144:147], v[210:213], v[68:71]
	v_mfma_f32_16x16x32_bf16 v[64:67], v[152:155], v[210:213], v[64:67]
	v_mfma_f32_16x16x32_bf16 v[128:131], v[148:151], v[178:181], v[128:131]
	v_mfma_f32_16x16x32_bf16 v[120:123], v[170:173], v[178:181], v[120:123]
	v_mfma_f32_16x16x32_bf16 v[104:107], v[148:151], v[198:201], v[104:107]
	v_mfma_f32_16x16x32_bf16 v[96:99], v[170:173], v[198:201], v[96:99]
	v_mfma_f32_16x16x32_bf16 v[84:87], v[148:151], v[206:209], v[84:87]
	v_mfma_f32_16x16x32_bf16 v[80:83], v[170:173], v[206:209], v[80:83]
	v_mfma_f32_16x16x32_bf16 v[68:71], v[148:151], v[214:217], v[68:71]
	v_mfma_f32_16x16x32_bf16 v[64:67], v[170:173], v[214:217], v[64:67]
	s_setprio 0
	s_barrier
; #define PG8_STAGE(bufoff, gbase, voff) do { _Pragma("unroll") for (int _i = 0; _i < 2; ++_i) \
;         __builtin_amdgcn_global_load_lds((const unsigned*)((const char*)(gbase) + (voff)[_i]), (LAS unsigned*)(lds + (bufoff) + ldsw + _i * 8192), 16, 0, 0); } while (0)
; #define PG8_LDA(dst, b, h) do { _Pragma("unroll") for (int m = 0; m < 4; ++m) _Pragma("unroll") for (int k = 0; k < 2; ++k) dst[m][k] = *(const LAS bf16x8*)(lds + PG8_SA(b, h) + aoff + m * 2048 + k * 1024); } while (0)
; #define PG8_MMA(ai, bj, At, Bt) do { __builtin_amdgcn_s_setprio(1); _Pragma("unroll") for (int m = 0; m < 4; ++m) _Pragma("unroll") for (int n = 0; n < 2; ++n) _Pragma("unroll") for (int k = 0; k < 2; ++k) \
;         acc[ai][bj][m][n] = __builtin_amdgcn_mfma_f32_16x16x32_bf16(Bt[n][k], At[m][k], acc[ai][bj][m][n], 0, 0, 0); __builtin_amdgcn_s_setprio(0); } while (0)
; #define PG8_WAIT_V(n) asm volatile("s_waitcnt vmcnt(" #n ")" ::: "memory")
; #define PG8_WAIT_L(n) asm volatile("s_waitcnt lgkmcnt(" #n ")" ::: "memory")
; #define PG8_BAR __builtin_amdgcn_s_barrier()
; #define PG8_SCHED __builtin_amdgcn_sched_barrier(0)
; template <class Epi, class Sched = StaticOrder, class EpiSub = NoSub, bool FAST = false>
; __device__ __forceinline__ void gemm_phase(LAS unsigned char* lds, const Gemm g, const Sched& S, const Epi& E, const EpiSub& ES = EpiSub()) {
;     ...
;             PG8_LDA(At, 1, 1); PG8_STAGE(PG8_SB(1, 0), b3, voffB); PG8_STAGE(PG8_SB(1, 1), b3 + hstepB, voffB); PG8_STAGE(PG8_SA(1, 0), a3, voffA);
;             PG8_WAIT_V(8); PG8_WAIT_L(0); PG8_BAR; PG8_MMA(1, 0, At, B0); PG8_MMA(1, 1, At, B1); PG8_BAR; PG8_SCHED;
;     ...
;         if constexpr (FAST && PG8_ALIGN) { if (wr == 0) PG8_BAR; }
	s_add_i32 s50, s50, s54
	v_lshl_add_u64 v[190:191], v[190:191], 0, s[12:13]
	s_mov_b32 m0, s50
	ds_read_b128 v[174:177], v188 offset:49152
	ds_read_b128 v[178:181], v188 offset:50176
	ds_read_b128 v[194:197], v188 offset:51200
	ds_read_b128 v[198:201], v188 offset:52224
	ds_read_b128 v[202:205], v188 offset:53248
	ds_read_b128 v[206:209], v188 offset:54272
	ds_read_b128 v[210:213], v188 offset:55296
	ds_read_b128 v[214:217], v188 offset:56320
	global_load_lds_dwordx4 v[190:191], off
	s_add_i32 m0, s50, 0x2000
	s_add_u32 s42, s42, 0x40080
	v_lshl_add_u64 v[190:191], v[218:219], 0, s[12:13]
	s_addc_u32 s43, s43, 0
	s_add_i32 s50, s70, s54
	global_load_lds_dwordx4 v[190:191], off
	v_lshl_add_u64 v[190:191], s[42:43], 0, v[158:159]
	s_mov_b32 m0, s50
	s_nop 0
	global_load_lds_dwordx4 v[190:191], off
	v_lshl_add_u64 v[190:191], s[42:43], 0, v[162:163]
	s_add_i32 m0, s50, 0x2000
	s_nop 0
	global_load_lds_dwordx4 v[190:191], off
	v_lshl_add_u64 v[190:191], v[220:221], 0, s[12:13]
	s_mov_b32 m0, s69
	s_nop 0
	global_load_lds_dwordx4 v[190:191], off
	v_lshl_add_u64 v[190:191], v[222:223], 0, s[12:13]
	s_mov_b32 m0, s74
	s_nop 0
	global_load_lds_dwordx4 v[190:191], off
	s_waitcnt vmcnt(8)
	s_waitcnt lgkmcnt(0)
	s_barrier
	s_setprio 1
	v_mfma_f32_16x16x32_bf16 v[60:63], v[100:103], v[174:177], v[60:63]
	v_mfma_f32_16x16x32_bf16 v[56:59], v[124:127], v[174:177], v[56:59]
	v_mfma_f32_16x16x32_bf16 v[44:47], v[100:103], v[194:197], v[44:47]
	v_mfma_f32_16x16x32_bf16 v[40:43], v[124:127], v[194:197], v[40:43]
	v_mfma_f32_16x16x32_bf16 v[28:31], v[100:103], v[202:205], v[28:31]
	v_mfma_f32_16x16x32_bf16 v[24:27], v[124:127], v[202:205], v[24:27]
	v_mfma_f32_16x16x32_bf16 v[12:15], v[100:103], v[210:213], v[12:15]
	v_mfma_f32_16x16x32_bf16 v[8:11], v[124:127], v[210:213], v[8:11]
	v_mfma_f32_16x16x32_bf16 v[60:63], v[112:115], v[178:181], v[60:63]
	v_mfma_f32_16x16x32_bf16 v[56:59], v[136:139], v[178:181], v[56:59]
	v_mfma_f32_16x16x32_bf16 v[44:47], v[112:115], v[198:201], v[44:47]
	v_mfma_f32_16x16x32_bf16 v[40:43], v[136:139], v[198:201], v[40:43]
	v_mfma_f32_16x16x32_bf16 v[28:31], v[112:115], v[206:209], v[28:31]
	v_mfma_f32_16x16x32_bf16 v[24:27], v[136:139], v[206:209], v[24:27]
	v_mfma_f32_16x16x32_bf16 v[12:15], v[112:115], v[214:217], v[12:15]
	v_mfma_f32_16x16x32_bf16 v[8:11], v[136:139], v[214:217], v[8:11]
	v_mfma_f32_16x16x32_bf16 v[52:55], v[144:147], v[174:177], v[52:55]
	v_mfma_f32_16x16x32_bf16 v[48:51], v[152:155], v[174:177], v[48:51]
	v_mfma_f32_16x16x32_bf16 v[36:39], v[144:147], v[194:197], v[36:39]
	v_mfma_f32_16x16x32_bf16 v[32:35], v[152:155], v[194:197], v[32:35]
	v_mfma_f32_16x16x32_bf16 v[20:23], v[144:147], v[202:205], v[20:23]
	v_mfma_f32_16x16x32_bf16 v[16:19], v[152:155], v[202:205], v[16:19]
	v_mfma_f32_16x16x32_bf16 v[4:7], v[144:147], v[210:213], v[4:7]
	v_mfma_f32_16x16x32_bf16 v[0:3], v[152:155], v[210:213], v[0:3]
	v_mfma_f32_16x16x32_bf16 v[52:55], v[148:151], v[178:181], v[52:55]
	v_mfma_f32_16x16x32_bf16 v[48:51], v[170:173], v[178:181], v[48:51]
	v_mfma_f32_16x16x32_bf16 v[36:39], v[148:151], v[198:201], v[36:39]
	v_mfma_f32_16x16x32_bf16 v[32:35], v[170:173], v[198:201], v[32:35]
	v_mfma_f32_16x16x32_bf16 v[20:23], v[148:151], v[206:209], v[20:23]
	v_mfma_f32_16x16x32_bf16 v[16:19], v[170:173], v[206:209], v[16:19]
	v_mfma_f32_16x16x32_bf16 v[4:7], v[148:151], v[214:217], v[4:7]
	v_mfma_f32_16x16x32_bf16 v[0:3], v[170:173], v[214:217], v[0:3]
	s_setprio 0
	s_barrier
	s_add_u32 s40, s40, 0x100
	s_addc_u32 s41, s41, 0
	s_add_u32 s48, s48, 0x100
	s_addc_u32 s49, s49, 0
	s_cmp_ge_u32 s51, s27
	s_mov_b32 s50, s51
	s_cbranch_scc0 .LBB0_600
	s_and_b64 vcc, exec, s[14:15]
	s_cbranch_vccz .LBB0_603
	s_barrier

; #define PG8_STAGE(bufoff, gbase, voff) do { _Pragma("unroll") for (int _i = 0; _i < 2; ++_i) \
;         __builtin_amdgcn_global_load_lds((const unsigned*)((const char*)(gbase) + (voff)[_i]), (LAS unsigned*)(lds + (bufoff) + ldsw + _i * 8192), 16, 0, 0); } while (0)
; #define PG8_LDA(dst, b, h) do { _Pragma("unroll") for (int m = 0; m < 4; ++m) _Pragma("unroll") for (int k = 0; k < 2; ++k) dst[m][k] = *(const LAS bf16x8*)(lds + PG8_SA(b, h) + aoff + m * 2048 + k * 1024); } while (0)
; #define PG8_LDB(dst, b, h) do { _Pragma("unroll") for (int n = 0; n < 2; ++n) _Pragma("unroll") for (int k = 0; k < 2; ++k) dst[n][k] = *(const LAS bf16x8*)(lds + PG8_SB(b, h) + boff + n * 2048 + k * 1024); } while (0)
; #define PG8_WAIT_V(n) asm volatile("s_waitcnt vmcnt(" #n ")" ::: "memory")
; #define PG8_BAR __builtin_amdgcn_s_barrier()
; template <class Epi, class Sched = StaticOrder, class EpiSub = NoSub, bool FAST = false>
; __device__ __forceinline__ void gemm_phase(LAS unsigned char* lds, const Gemm g, const Sched& S, const Epi& E, const EpiSub& ES = EpiSub()) {
;     ...
;         const bool has_next = S.next(ui + 1, nxt);
;         const size_t nko = (has_next && nxt.kb >= 0) ? nxt.kb * ksubB : 0;
;         const char* nA = has_next ? (const char*)g.A + (size_t)nxt.pm * tstepA + (size_t)nxt.pn * g.acs + nko : cA; const char* nB = has_next ? (const char*)g.Bt + (size_t)nxt.pn * tstepB + nko : cB;
;         const int nt = cur.kb < 0 ? ntMain : ntSub;
;         for (int t = 0; t < nt; t += 2) {
;             const bool last = (t == nt - 2);
;             const char* a1 = cA + (size_t)(t + 1) * kstep;
;             const char* a2 = last ? nA : cA + (size_t)(t + 2) * kstep; const char* b2 = last ? nB : cB + (size_t)(t + 2) * kstep;
;             const char* a3 = a2 + kstep; const char* b3 = b2 + kstep;
;             if constexpr (FAST && PG8_SP2) {
;             PG8_LDB(B0, 0, 0); PG8_LDB(B1, 0, 1); PG8_SCHED; PG8_LDA(At, 0, 0); PG8_STAGE(PG8_SA(1, 1), a1 + hstepA, voffA);
;             PG8_WAIT_V(8); PG8_WAIT_L(0); PG8_BAR; PG8_MMA(0, 0, At, B0); PG8_MMA(0, 1, At, B1); PG8_BAR; PG8_SCHED;
;             PG8_LDA(At, 0, 1); PG8_STAGE(PG8_SB(0, 0), b2, voffB); PG8_STAGE(PG8_SB(0, 1), b2 + hstepB, voffB); PG8_STAGE(PG8_SA(0, 0), a2, voffA);
;             PG8_WAIT_V(8); PG8_WAIT_L(0); PG8_BAR; PG8_MMA(1, 0, At, B0); PG8_MMA(1, 1, At, B1); PG8_BAR; PG8_SCHED;
.LBB0_632:
	ds_read_b128 v[104:107], v224
	ds_read_b128 v[108:111], v224 offset:1024
	ds_read_b128 v[120:123], v224 offset:2048
	ds_read_b128 v[124:127], v224 offset:3072
	ds_read_b128 v[136:139], v225
	ds_read_b128 v[140:143], v225 offset:1024
	ds_read_b128 v[152:155], v225 offset:2048
	ds_read_b128 v[156:159], v225 offset:3072
	s_add_i32 s50, s42, 2
	s_add_u32 s40, s38, 0xfff80080
	s_addc_u32 s41, s39, -1
	s_cmp_eq_u32 s33, s42
	s_cselect_b32 s42, s5, s40
	s_cselect_b32 s43, s1, s41
	s_cselect_b32 s41, s21, s49
	s_cselect_b32 s40, s23, s48
	v_lshl_add_u64 v[208:209], s[38:39], 0, v[202:203]
	s_add_i32 m0, s53, 0xc000
	ds_read_b128 v[160:163], v226
	ds_read_b128 v[164:167], v226 offset:1024
	ds_read_b128 v[168:171], v226 offset:2048
	ds_read_b128 v[172:175], v226 offset:3072
	ds_read_b128 v[176:179], v226 offset:4096
	ds_read_b128 v[180:183], v226 offset:5120
	ds_read_b128 v[184:187], v226 offset:6144
	ds_read_b128 v[188:191], v226 offset:7168
	global_load_lds_dwordx4 v[208:209], off
	v_lshl_add_u64 v[208:209], s[38:39], 0, v[204:205]
	s_add_i32 m0, s53, 0xe000
	s_nop 0
	global_load_lds_dwordx4 v[208:209], off
	s_waitcnt vmcnt(8)
	s_waitcnt lgkmcnt(0)
	s_barrier
	s_setprio 1
	v_mfma_f32_16x16x32_bf16 v[148:151], v[104:107], v[160:163], v[148:151]
	v_mfma_f32_16x16x32_bf16 v[144:147], v[120:123], v[160:163], v[144:147]
	v_mfma_f32_16x16x32_bf16 v[116:119], v[104:107], v[168:171], v[116:119]
	v_mfma_f32_16x16x32_bf16 v[112:115], v[120:123], v[168:171], v[112:115]
	v_mfma_f32_16x16x32_bf16 v[92:95], v[104:107], v[176:179], v[92:95]
	v_mfma_f32_16x16x32_bf16 v[88:91], v[120:123], v[176:179], v[88:91]
	v_mfma_f32_16x16x32_bf16 v[76:79], v[104:107], v[184:187], v[76:79]
	v_mfma_f32_16x16x32_bf16 v[72:75], v[120:123], v[184:187], v[72:75]
	v_mfma_f32_16x16x32_bf16 v[148:151], v[108:111], v[164:167], v[148:151]
	v_mfma_f32_16x16x32_bf16 v[144:147], v[124:127], v[164:167], v[144:147]
	v_mfma_f32_16x16x32_bf16 v[116:119], v[108:111], v[172:175], v[116:119]
	v_mfma_f32_16x16x32_bf16 v[112:115], v[124:127], v[172:175], v[112:115]
	v_mfma_f32_16x16x32_bf16 v[92:95], v[108:111], v[180:183], v[92:95]
	v_mfma_f32_16x16x32_bf16 v[88:91], v[124:127], v[180:183], v[88:91]
	v_mfma_f32_16x16x32_bf16 v[76:79], v[108:111], v[188:191], v[76:79]
	v_mfma_f32_16x16x32_bf16 v[72:75], v[124:127], v[188:191], v[72:75]
	v_mfma_f32_16x16x32_bf16 v[132:135], v[136:139], v[160:163], v[132:135]
	v_mfma_f32_16x16x32_bf16 v[128:131], v[152:155], v[160:163], v[128:131]
	v_mfma_f32_16x16x32_bf16 v[100:103], v[136:139], v[168:171], v[100:103]
	v_mfma_f32_16x16x32_bf16 v[96:99], v[152:155], v[168:171], v[96:99]
	v_mfma_f32_16x16x32_bf16 v[84:87], v[136:139], v[176:179], v[84:87]
	v_mfma_f32_16x16x32_bf16 v[80:83], v[152:155], v[176:179], v[80:83]
	v_mfma_f32_16x16x32_bf16 v[68:71], v[136:139], v[184:187], v[68:71]
	v_mfma_f32_16x16x32_bf16 v[64:67], v[152:155], v[184:187], v[64:67]
	v_mfma_f32_16x16x32_bf16 v[132:135], v[140:143], v[164:167], v[132:135]
	v_mfma_f32_16x16x32_bf16 v[128:131], v[156:159], v[164:167], v[128:131]
	v_mfma_f32_16x16x32_bf16 v[100:103], v[140:143], v[172:175], v[100:103]
	v_mfma_f32_16x16x32_bf16 v[96:99], v[156:159], v[172:175], v[96:99]
	v_mfma_f32_16x16x32_bf16 v[84:87], v[140:143], v[180:183], v[84:87]
	v_mfma_f32_16x16x32_bf16 v[80:83], v[156:159], v[180:183], v[80:83]
	v_mfma_f32_16x16x32_bf16 v[68:71], v[140:143], v[188:191], v[68:71]
	v_mfma_f32_16x16x32_bf16 v[64:67], v[156:159], v[188:191], v[64:67]
	s_setprio 0
	s_barrier
	s_add_i32 s51, s75, s52
	v_lshl_add_u64 v[208:209], s[40:41], 0, v[196:197]
	s_mov_b32 m0, s51
	ds_read_b128 v[160:163], v226 offset:16384
	ds_read_b128 v[164:167], v226 offset:17408
	ds_read_b128 v[168:171], v226 offset:18432
	ds_read_b128 v[172:175], v226 offset:19456
	ds_read_b128 v[176:179], v226 offset:20480
	ds_read_b128 v[180:183], v226 offset:21504
	ds_read_b128 v[184:187], v226 offset:22528
	ds_read_b128 v[188:191], v226 offset:23552
	global_load_lds_dwordx4 v[208:209], off
	s_add_i32 m0, s51, 0x2000
	s_add_u32 s70, s40, 0x80000
	v_lshl_add_u64 v[210:211], s[40:41], 0, v[200:201]
	s_addc_u32 s71, s41, 0
	s_add_i32 s51, s78, s52
	global_load_lds_dwordx4 v[210:211], off
	v_lshl_add_u64 v[212:213], s[70:71], 0, v[196:197]
	s_mov_b32 m0, s51
	v_lshl_add_u64 v[214:215], s[42:43], 0, v[198:199]
	global_load_lds_dwordx4 v[212:213], off
	v_lshl_add_u64 v[212:213], s[70:71], 0, v[200:201]
	s_add_i32 m0, s51, 0x2000
	s_nop 0
	global_load_lds_dwordx4 v[212:213], off
	v_lshl_add_u64 v[212:213], s[42:43], 0, v[194:195]
	s_mov_b32 m0, s53
	s_nop 0
	global_load_lds_dwordx4 v[212:213], off
	s_mov_b32 m0, s54
	s_nop 0
	global_load_lds_dwordx4 v[214:215], off
	s_waitcnt vmcnt(8)
	s_waitcnt lgkmcnt(0)
	s_barrier
; #define PG8_STAGE(bufoff, gbase, voff) do { _Pragma("unroll") for (int _i = 0; _i < 2; ++_i) \
;         __builtin_amdgcn_global_load_lds((const unsigned*)((const char*)(gbase) + (voff)[_i]), (LAS unsigned*)(lds + (bufoff) + ldsw + _i * 8192), 16, 0, 0); } while (0)
; #define PG8_LDA(dst, b, h) do { _Pragma("unroll") for (int m = 0; m < 4; ++m) _Pragma("unroll") for (int k = 0; k < 2; ++k) dst[m][k] = *(const LAS bf16x8*)(lds + PG8_SA(b, h) + aoff + m * 2048 + k * 1024); } while (0)
; #define PG8_LDB(dst, b, h) do { _Pragma("unroll") for (int n = 0; n < 2; ++n) _Pragma("unroll") for (int k = 0; k < 2; ++k) dst[n][k] = *(const LAS bf16x8*)(lds + PG8_SB(b, h) + boff + n * 2048 + k * 1024); } while (0)
; #define PG8_MMA(ai, bj, At, Bt) do { __builtin_amdgcn_s_setprio(1); _Pragma("unroll") for (int m = 0; m < 4; ++m) _Pragma("unroll") for (int n = 0; n < 2; ++n) _Pragma("unroll") for (int k = 0; k < 2; ++k) \
;         acc[ai][bj][m][n] = __builtin_amdgcn_mfma_f32_16x16x32_bf16(Bt[n][k], At[m][k], acc[ai][bj][m][n], 0, 0, 0); __builtin_amdgcn_s_setprio(0); } while (0)
; #define PG8_WAIT_V(n) asm volatile("s_waitcnt vmcnt(" #n ")" ::: "memory")
; #define PG8_WAIT_L(n) asm volatile("s_waitcnt lgkmcnt(" #n ")" ::: "memory")
; #define PG8_BAR __builtin_amdgcn_s_barrier()
; #define PG8_SCHED __builtin_amdgcn_sched_barrier(0)
; template <class Epi, class Sched = StaticOrder, class EpiSub = NoSub, bool FAST = false>
; __device__ __forceinline__ void gemm_phase(LAS unsigned char* lds, const Gemm g, const Sched& S, const Epi& E, const EpiSub& ES = EpiSub()) {
;     ...
;             PG8_WAIT_V(8); PG8_WAIT_L(0); PG8_BAR; PG8_MMA(1, 0, At, B0); PG8_MMA(1, 1, At, B1); PG8_BAR; PG8_SCHED;
;             PG8_LDB(B0, 1, 0); PG8_LDB(B1, 1, 1); PG8_SCHED; PG8_LDA(At, 1, 0); PG8_STAGE(PG8_SA(0, 1), a2 + hstepA, voffA);
;             PG8_WAIT_V(8); PG8_WAIT_L(0); PG8_BAR; PG8_MMA(0, 0, At, B0); PG8_MMA(0, 1, At, B1); PG8_BAR; PG8_SCHED;
	s_setprio 1
	v_mfma_f32_16x16x32_bf16 v[60:63], v[104:107], v[160:163], v[60:63]
	v_mfma_f32_16x16x32_bf16 v[56:59], v[120:123], v[160:163], v[56:59]
	v_mfma_f32_16x16x32_bf16 v[44:47], v[104:107], v[168:171], v[44:47]
	v_mfma_f32_16x16x32_bf16 v[40:43], v[120:123], v[168:171], v[40:43]
	v_mfma_f32_16x16x32_bf16 v[28:31], v[104:107], v[176:179], v[28:31]
	v_mfma_f32_16x16x32_bf16 v[24:27], v[120:123], v[176:179], v[24:27]
	v_mfma_f32_16x16x32_bf16 v[12:15], v[104:107], v[184:187], v[12:15]
	v_mfma_f32_16x16x32_bf16 v[8:11], v[120:123], v[184:187], v[8:11]
	v_mfma_f32_16x16x32_bf16 v[60:63], v[108:111], v[164:167], v[60:63]
	v_mfma_f32_16x16x32_bf16 v[56:59], v[124:127], v[164:167], v[56:59]
	v_mfma_f32_16x16x32_bf16 v[44:47], v[108:111], v[172:175], v[44:47]
	v_mfma_f32_16x16x32_bf16 v[40:43], v[124:127], v[172:175], v[40:43]
	v_mfma_f32_16x16x32_bf16 v[28:31], v[108:111], v[180:183], v[28:31]
	v_mfma_f32_16x16x32_bf16 v[24:27], v[124:127], v[180:183], v[24:27]
	v_mfma_f32_16x16x32_bf16 v[12:15], v[108:111], v[188:191], v[12:15]
	v_mfma_f32_16x16x32_bf16 v[8:11], v[124:127], v[188:191], v[8:11]
	v_mfma_f32_16x16x32_bf16 v[52:55], v[136:139], v[160:163], v[52:55]
	v_mfma_f32_16x16x32_bf16 v[48:51], v[152:155], v[160:163], v[48:51]
	v_mfma_f32_16x16x32_bf16 v[36:39], v[136:139], v[168:171], v[36:39]
	v_mfma_f32_16x16x32_bf16 v[32:35], v[152:155], v[168:171], v[32:35]
	v_mfma_f32_16x16x32_bf16 v[20:23], v[136:139], v[176:179], v[20:23]
	v_mfma_f32_16x16x32_bf16 v[16:19], v[152:155], v[176:179], v[16:19]
	v_mfma_f32_16x16x32_bf16 v[4:7], v[136:139], v[184:187], v[4:7]
	v_mfma_f32_16x16x32_bf16 v[0:3], v[152:155], v[184:187], v[0:3]
	v_mfma_f32_16x16x32_bf16 v[52:55], v[140:143], v[164:167], v[52:55]
	v_mfma_f32_16x16x32_bf16 v[48:51], v[156:159], v[164:167], v[48:51]
	v_mfma_f32_16x16x32_bf16 v[36:39], v[140:143], v[172:175], v[36:39]
	v_mfma_f32_16x16x32_bf16 v[32:35], v[156:159], v[172:175], v[32:35]
	v_mfma_f32_16x16x32_bf16 v[20:23], v[140:143], v[180:183], v[20:23]
	v_mfma_f32_16x16x32_bf16 v[16:19], v[156:159], v[180:183], v[16:19]
	v_mfma_f32_16x16x32_bf16 v[4:7], v[140:143], v[188:191], v[4:7]
	v_mfma_f32_16x16x32_bf16 v[0:3], v[156:159], v[188:191], v[0:3]
	s_setprio 0
	s_barrier
	s_add_i32 s51, 0, 0x18000
	s_add_i32 s70, 0, 0x1c000
	v_add_u32_e32 v124, s51, v221
	v_add_u32_e32 v156, s70, v221
	ds_read_b128 v[104:107], v124
	ds_read_b128 v[108:111], v124 offset:1024
	ds_read_b128 v[120:123], v124 offset:2048
	ds_read_b128 v[124:127], v124 offset:3072
	ds_read_b128 v[136:139], v156
	ds_read_b128 v[140:143], v156 offset:1024
	ds_read_b128 v[152:155], v156 offset:2048
	ds_read_b128 v[156:159], v156 offset:3072
	s_add_u32 s42, s42, 0x80000
	s_addc_u32 s43, s43, 0
	s_mov_b32 m0, s55
	v_lshl_add_u64 v[216:217], s[42:43], 0, v[194:195]
	ds_read_b128 v[160:163], v226 offset:32768
	ds_read_b128 v[164:167], v226 offset:33792
	ds_read_b128 v[168:171], v226 offset:34816
	ds_read_b128 v[172:175], v226 offset:35840
	ds_read_b128 v[176:179], v226 offset:36864
	ds_read_b128 v[180:183], v226 offset:37888
	ds_read_b128 v[184:187], v226 offset:38912
	ds_read_b128 v[188:191], v226 offset:39936
	global_load_lds_dwordx4 v[216:217], off
	v_lshl_add_u64 v[216:217], s[42:43], 0, v[198:199]
	s_mov_b32 m0, s56
	s_nop 0
	global_load_lds_dwordx4 v[216:217], off
	s_waitcnt vmcnt(8)
	s_waitcnt lgkmcnt(0)
	s_barrier
	s_setprio 1
	v_mfma_f32_16x16x32_bf16 v[148:151], v[104:107], v[160:163], v[148:151]
	v_mfma_f32_16x16x32_bf16 v[144:147], v[120:123], v[160:163], v[144:147]
	v_mfma_f32_16x16x32_bf16 v[116:119], v[104:107], v[168:171], v[116:119]
	v_mfma_f32_16x16x32_bf16 v[112:115], v[120:123], v[168:171], v[112:115]
	v_mfma_f32_16x16x32_bf16 v[92:95], v[104:107], v[176:179], v[92:95]
	v_mfma_f32_16x16x32_bf16 v[88:91], v[120:123], v[176:179], v[88:91]
	v_mfma_f32_16x16x32_bf16 v[76:79], v[104:107], v[184:187], v[76:79]
	v_mfma_f32_16x16x32_bf16 v[72:75], v[120:123], v[184:187], v[72:75]
	v_mfma_f32_16x16x32_bf16 v[148:151], v[108:111], v[164:167], v[148:151]
	v_mfma_f32_16x16x32_bf16 v[144:147], v[124:127], v[164:167], v[144:147]
	v_mfma_f32_16x16x32_bf16 v[116:119], v[108:111], v[172:175], v[116:119]
	v_mfma_f32_16x16x32_bf16 v[112:115], v[124:127], v[172:175], v[112:115]
	v_mfma_f32_16x16x32_bf16 v[92:95], v[108:111], v[180:183], v[92:95]
	v_mfma_f32_16x16x32_bf16 v[88:91], v[124:127], v[180:183], v[88:91]
	v_mfma_f32_16x16x32_bf16 v[76:79], v[108:111], v[188:191], v[76:79]
	v_mfma_f32_16x16x32_bf16 v[72:75], v[124:127], v[188:191], v[72:75]
	v_mfma_f32_16x16x32_bf16 v[132:135], v[136:139], v[160:163], v[132:135]
	v_mfma_f32_16x16x32_bf16 v[128:131], v[152:155], v[160:163], v[128:131]
	v_mfma_f32_16x16x32_bf16 v[100:103], v[136:139], v[168:171], v[100:103]
	v_mfma_f32_16x16x32_bf16 v[96:99], v[152:155], v[168:171], v[96:99]
	v_mfma_f32_16x16x32_bf16 v[84:87], v[136:139], v[176:179], v[84:87]
	v_mfma_f32_16x16x32_bf16 v[80:83], v[152:155], v[176:179], v[80:83]
	v_mfma_f32_16x16x32_bf16 v[68:71], v[136:139], v[184:187], v[68:71]
	v_mfma_f32_16x16x32_bf16 v[64:67], v[152:155], v[184:187], v[64:67]
	v_mfma_f32_16x16x32_bf16 v[132:135], v[140:143], v[164:167], v[132:135]
	v_mfma_f32_16x16x32_bf16 v[128:131], v[156:159], v[164:167], v[128:131]
	v_mfma_f32_16x16x32_bf16 v[100:103], v[140:143], v[172:175], v[100:103]
	v_mfma_f32_16x16x32_bf16 v[96:99], v[156:159], v[172:175], v[96:99]
	v_mfma_f32_16x16x32_bf16 v[84:87], v[140:143], v[180:183], v[84:87]
	v_mfma_f32_16x16x32_bf16 v[80:83], v[156:159], v[180:183], v[80:83]
	v_mfma_f32_16x16x32_bf16 v[68:71], v[140:143], v[188:191], v[68:71]
	v_mfma_f32_16x16x32_bf16 v[64:67], v[156:159], v[188:191], v[64:67]
	s_setprio 0
	s_barrier
; #define PG8_STAGE(bufoff, gbase, voff) do { _Pragma("unroll") for (int _i = 0; _i < 2; ++_i) \
;         __builtin_amdgcn_global_load_lds((const unsigned*)((const char*)(gbase) + (voff)[_i]), (LAS unsigned*)(lds + (bufoff) + ldsw + _i * 8192), 16, 0, 0); } while (0)
; #define PG8_LDA(dst, b, h) do { _Pragma("unroll") for (int m = 0; m < 4; ++m) _Pragma("unroll") for (int k = 0; k < 2; ++k) dst[m][k] = *(const LAS bf16x8*)(lds + PG8_SA(b, h) + aoff + m * 2048 + k * 1024); } while (0)
; #define PG8_MMA(ai, bj, At, Bt) do { __builtin_amdgcn_s_setprio(1); _Pragma("unroll") for (int m = 0; m < 4; ++m) _Pragma("unroll") for (int n = 0; n < 2; ++n) _Pragma("unroll") for (int k = 0; k < 2; ++k) \
;         acc[ai][bj][m][n] = __builtin_amdgcn_mfma_f32_16x16x32_bf16(Bt[n][k], At[m][k], acc[ai][bj][m][n], 0, 0, 0); __builtin_amdgcn_s_setprio(0); } while (0)
; #define PG8_WAIT_V(n) asm volatile("s_waitcnt vmcnt(" #n ")" ::: "memory")
; #define PG8_WAIT_L(n) asm volatile("s_waitcnt lgkmcnt(" #n ")" ::: "memory")
; #define PG8_BAR __builtin_amdgcn_s_barrier()
; #define PG8_SCHED __builtin_amdgcn_sched_barrier(0)
; template <class Epi, class Sched = StaticOrder, class EpiSub = NoSub, bool FAST = false>
; __device__ __forceinline__ void gemm_phase(LAS unsigned char* lds, const Gemm g, const Sched& S, const Epi& E, const EpiSub& ES = EpiSub()) {
;     ...
;             PG8_LDA(At, 1, 1); PG8_STAGE(PG8_SB(1, 0), b3, voffB); PG8_STAGE(PG8_SB(1, 1), b3 + hstepB, voffB); PG8_STAGE(PG8_SA(1, 0), a3, voffA);
;             PG8_WAIT_V(8); PG8_WAIT_L(0); PG8_BAR; PG8_MMA(1, 0, At, B0); PG8_MMA(1, 1, At, B1); PG8_BAR; PG8_SCHED;
;     ...
;         if constexpr (FAST && PG8_ALIGN) { if (wr == 0) PG8_BAR; }
	s_add_i32 s42, s51, s52
	v_lshl_add_u64 v[208:209], v[208:209], 0, s[12:13]
	s_mov_b32 m0, s42
	ds_read_b128 v[160:163], v226 offset:49152
	ds_read_b128 v[164:167], v226 offset:50176
	ds_read_b128 v[168:171], v226 offset:51200
	ds_read_b128 v[172:175], v226 offset:52224
	ds_read_b128 v[176:179], v226 offset:53248
	ds_read_b128 v[180:183], v226 offset:54272
	ds_read_b128 v[184:187], v226 offset:55296
	ds_read_b128 v[188:191], v226 offset:56320
	global_load_lds_dwordx4 v[208:209], off
	s_add_i32 m0, s42, 0x2000
	s_add_u32 s40, s40, 0x80080
	v_lshl_add_u64 v[208:209], v[210:211], 0, s[12:13]
	s_addc_u32 s41, s41, 0
	s_add_i32 s42, s70, s52
	global_load_lds_dwordx4 v[208:209], off
	v_lshl_add_u64 v[208:209], s[40:41], 0, v[196:197]
	s_mov_b32 m0, s42
	s_nop 0
	global_load_lds_dwordx4 v[208:209], off
	v_lshl_add_u64 v[208:209], s[40:41], 0, v[200:201]
	s_add_i32 m0, s42, 0x2000
	s_nop 0
	global_load_lds_dwordx4 v[208:209], off
	v_lshl_add_u64 v[208:209], v[212:213], 0, s[12:13]
	s_mov_b32 m0, s69
	s_nop 0
	global_load_lds_dwordx4 v[208:209], off
	v_lshl_add_u64 v[208:209], v[214:215], 0, s[12:13]
	s_mov_b32 m0, s74
	s_nop 0
	global_load_lds_dwordx4 v[208:209], off
	s_waitcnt vmcnt(8)
	s_waitcnt lgkmcnt(0)
	s_barrier
	s_setprio 1
	v_mfma_f32_16x16x32_bf16 v[60:63], v[104:107], v[160:163], v[60:63]
	v_mfma_f32_16x16x32_bf16 v[56:59], v[120:123], v[160:163], v[56:59]
	v_mfma_f32_16x16x32_bf16 v[44:47], v[104:107], v[168:171], v[44:47]
	v_mfma_f32_16x16x32_bf16 v[40:43], v[120:123], v[168:171], v[40:43]
	v_mfma_f32_16x16x32_bf16 v[28:31], v[104:107], v[176:179], v[28:31]
	v_mfma_f32_16x16x32_bf16 v[24:27], v[120:123], v[176:179], v[24:27]
	v_mfma_f32_16x16x32_bf16 v[12:15], v[104:107], v[184:187], v[12:15]
	v_mfma_f32_16x16x32_bf16 v[8:11], v[120:123], v[184:187], v[8:11]
	v_mfma_f32_16x16x32_bf16 v[60:63], v[108:111], v[164:167], v[60:63]
	v_mfma_f32_16x16x32_bf16 v[56:59], v[124:127], v[164:167], v[56:59]
	v_mfma_f32_16x16x32_bf16 v[44:47], v[108:111], v[172:175], v[44:47]
	v_mfma_f32_16x16x32_bf16 v[40:43], v[124:127], v[172:175], v[40:43]
	v_mfma_f32_16x16x32_bf16 v[28:31], v[108:111], v[180:183], v[28:31]
	v_mfma_f32_16x16x32_bf16 v[24:27], v[124:127], v[180:183], v[24:27]
	v_mfma_f32_16x16x32_bf16 v[12:15], v[108:111], v[188:191], v[12:15]
	v_mfma_f32_16x16x32_bf16 v[8:11], v[124:127], v[188:191], v[8:11]
	v_mfma_f32_16x16x32_bf16 v[52:55], v[136:139], v[160:163], v[52:55]
	v_mfma_f32_16x16x32_bf16 v[48:51], v[152:155], v[160:163], v[48:51]
	v_mfma_f32_16x16x32_bf16 v[36:39], v[136:139], v[168:171], v[36:39]
	v_mfma_f32_16x16x32_bf16 v[32:35], v[152:155], v[168:171], v[32:35]
	v_mfma_f32_16x16x32_bf16 v[20:23], v[136:139], v[176:179], v[20:23]
	v_mfma_f32_16x16x32_bf16 v[16:19], v[152:155], v[176:179], v[16:19]
	v_mfma_f32_16x16x32_bf16 v[4:7], v[136:139], v[184:187], v[4:7]
	v_mfma_f32_16x16x32_bf16 v[0:3], v[152:155], v[184:187], v[0:3]
	v_mfma_f32_16x16x32_bf16 v[52:55], v[140:143], v[164:167], v[52:55]
	v_mfma_f32_16x16x32_bf16 v[48:51], v[156:159], v[164:167], v[48:51]
	v_mfma_f32_16x16x32_bf16 v[36:39], v[140:143], v[172:175], v[36:39]
	v_mfma_f32_16x16x32_bf16 v[32:35], v[156:159], v[172:175], v[32:35]
	v_mfma_f32_16x16x32_bf16 v[20:23], v[140:143], v[180:183], v[20:23]
	v_mfma_f32_16x16x32_bf16 v[16:19], v[156:159], v[180:183], v[16:19]
	v_mfma_f32_16x16x32_bf16 v[4:7], v[140:143], v[188:191], v[4:7]
	v_mfma_f32_16x16x32_bf16 v[0:3], v[156:159], v[188:191], v[0:3]
	s_setprio 0
	s_barrier
	s_add_u32 s38, s38, 0x100
	s_addc_u32 s39, s39, 0
	s_add_u32 s48, s48, 0x100
	s_addc_u32 s49, s49, 0
	s_cmp_ge_u32 s50, s31
	s_mov_b32 s42, s50
	s_cbranch_scc0 .LBB0_632
	s_and_b64 vcc, exec, s[14:15]
	s_cbranch_vccz .LBB0_635
	s_barrier

; #define PG8_STAGE(bufoff, gbase, voff) do { _Pragma("unroll") for (int _i = 0; _i < 2; ++_i) \
;         __builtin_amdgcn_global_load_lds((const unsigned*)((const char*)(gbase) + (voff)[_i]), (LAS unsigned*)(lds + (bufoff) + ldsw + _i * 8192), 16, 0, 0); } while (0)
; #define PG8_LDA(dst, b, h) do { _Pragma("unroll") for (int m = 0; m < 4; ++m) _Pragma("unroll") for (int k = 0; k < 2; ++k) dst[m][k] = *(const LAS bf16x8*)(lds + PG8_SA(b, h) + aoff + m * 2048 + k * 1024); } while (0)
; #define PG8_LDB(dst, b, h) do { _Pragma("unroll") for (int n = 0; n < 2; ++n) _Pragma("unroll") for (int k = 0; k < 2; ++k) dst[n][k] = *(const LAS bf16x8*)(lds + PG8_SB(b, h) + boff + n * 2048 + k * 1024); } while (0)
; #define PG8_WAIT_V(n) asm volatile("s_waitcnt vmcnt(" #n ")" ::: "memory")
; #define PG8_BAR __builtin_amdgcn_s_barrier()
; template <class Epi, class Sched = StaticOrder, class EpiSub = NoSub, bool FAST = false>
; __device__ __forceinline__ void gemm_phase(LAS unsigned char* lds, const Gemm g, const Sched& S, const Epi& E, const EpiSub& ES = EpiSub()) {
;     ...
;         const bool has_next = S.next(ui + 1, nxt);
;         const size_t nko = (has_next && nxt.kb >= 0) ? nxt.kb * ksubB : 0;
;         const char* nA = has_next ? (const char*)g.A + (size_t)nxt.pm * tstepA + (size_t)nxt.pn * g.acs + nko : cA; const char* nB = has_next ? (const char*)g.Bt + (size_t)nxt.pn * tstepB + nko : cB;
;         const int nt = cur.kb < 0 ? ntMain : ntSub;
;         for (int t = 0; t < nt; t += 2) {
;             const bool last = (t == nt - 2);
;             const char* a1 = cA + (size_t)(t + 1) * kstep;
;             const char* a2 = last ? nA : cA + (size_t)(t + 2) * kstep; const char* b2 = last ? nB : cB + (size_t)(t + 2) * kstep;
;             const char* a3 = a2 + kstep; const char* b3 = b2 + kstep;
;             if constexpr (FAST && PG8_SP2) {
;             PG8_LDB(B0, 0, 0); PG8_LDB(B1, 0, 1); PG8_SCHED; PG8_LDA(At, 0, 0); PG8_STAGE(PG8_SA(1, 1), a1 + hstepA, voffA);
;             PG8_WAIT_V(8); PG8_WAIT_L(0); PG8_BAR; PG8_MMA(0, 0, At, B0); PG8_MMA(0, 1, At, B1); PG8_BAR; PG8_SCHED;
;             PG8_LDA(At, 0, 1); PG8_STAGE(PG8_SB(0, 0), b2, voffB); PG8_STAGE(PG8_SB(0, 1), b2 + hstepB, voffB); PG8_STAGE(PG8_SA(0, 0), a2, voffA);
;             PG8_WAIT_V(8); PG8_WAIT_L(0); PG8_BAR; PG8_MMA(1, 0, At, B0); PG8_MMA(1, 1, At, B1); PG8_BAR; PG8_SCHED;
.LBB0_769:
	ds_read_b128 v[96:99], v215
	ds_read_b128 v[100:103], v215 offset:1024
	ds_read_b128 v[112:115], v215 offset:2048
	ds_read_b128 v[116:119], v215 offset:3072
	ds_read_b128 v[144:147], v216
	ds_read_b128 v[148:151], v216 offset:1024
	ds_read_b128 v[152:155], v216 offset:2048
	ds_read_b128 v[156:159], v216 offset:3072
	s_add_i32 s72, s42, 2
	s_add_u32 s40, s38, 0xfff80080
	s_addc_u32 s41, s39, -1
	s_cmp_eq_u32 s33, s42
	s_cselect_b32 s42, s5, s40
	s_cselect_b32 s43, s1, s41
	s_cselect_b32 s41, s19, s71
	s_cselect_b32 s40, s21, s70
	v_lshl_add_u64 v[208:209], s[38:39], 0, v[194:195]
	s_add_i32 m0, s48, 0xc000
	ds_read_b128 v[160:163], v217
	ds_read_b128 v[164:167], v217 offset:1024
	ds_read_b128 v[168:171], v217 offset:2048
	ds_read_b128 v[172:175], v217 offset:3072
	ds_read_b128 v[176:179], v217 offset:4096
	ds_read_b128 v[180:183], v217 offset:5120
	ds_read_b128 v[200:203], v217 offset:6144
	ds_read_b128 v[204:207], v217 offset:7168
	global_load_lds_dwordx4 v[208:209], off
	v_lshl_add_u64 v[208:209], s[38:39], 0, v[196:197]
	s_add_i32 m0, s48, 0xe000
	s_nop 0
	global_load_lds_dwordx4 v[208:209], off
	s_waitcnt vmcnt(8)
	s_waitcnt lgkmcnt(0)
	s_barrier
	s_setprio 1
	v_mfma_f32_16x16x32_bf16 v[140:143], v[96:99], v[160:163], v[140:143]
	v_mfma_f32_16x16x32_bf16 v[136:139], v[112:115], v[160:163], v[136:139]
	v_mfma_f32_16x16x32_bf16 v[124:127], v[96:99], v[168:171], v[124:127]
	v_mfma_f32_16x16x32_bf16 v[120:123], v[112:115], v[168:171], v[120:123]
	v_mfma_f32_16x16x32_bf16 v[92:95], v[96:99], v[176:179], v[92:95]
	v_mfma_f32_16x16x32_bf16 v[88:91], v[112:115], v[176:179], v[88:91]
	v_mfma_f32_16x16x32_bf16 v[76:79], v[96:99], v[200:203], v[76:79]
	v_mfma_f32_16x16x32_bf16 v[72:75], v[112:115], v[200:203], v[72:75]
	v_mfma_f32_16x16x32_bf16 v[140:143], v[100:103], v[164:167], v[140:143]
	v_mfma_f32_16x16x32_bf16 v[136:139], v[116:119], v[164:167], v[136:139]
	v_mfma_f32_16x16x32_bf16 v[124:127], v[100:103], v[172:175], v[124:127]
	v_mfma_f32_16x16x32_bf16 v[120:123], v[116:119], v[172:175], v[120:123]
	v_mfma_f32_16x16x32_bf16 v[92:95], v[100:103], v[180:183], v[92:95]
	v_mfma_f32_16x16x32_bf16 v[88:91], v[116:119], v[180:183], v[88:91]
	v_mfma_f32_16x16x32_bf16 v[76:79], v[100:103], v[204:207], v[76:79]
	v_mfma_f32_16x16x32_bf16 v[72:75], v[116:119], v[204:207], v[72:75]
	v_mfma_f32_16x16x32_bf16 v[132:135], v[144:147], v[160:163], v[132:135]
	v_mfma_f32_16x16x32_bf16 v[128:131], v[152:155], v[160:163], v[128:131]
	v_mfma_f32_16x16x32_bf16 v[108:111], v[144:147], v[168:171], v[108:111]
	v_mfma_f32_16x16x32_bf16 v[104:107], v[152:155], v[168:171], v[104:107]
	v_mfma_f32_16x16x32_bf16 v[84:87], v[144:147], v[176:179], v[84:87]
	v_mfma_f32_16x16x32_bf16 v[80:83], v[152:155], v[176:179], v[80:83]
	v_mfma_f32_16x16x32_bf16 v[68:71], v[144:147], v[200:203], v[68:71]
	v_mfma_f32_16x16x32_bf16 v[64:67], v[152:155], v[200:203], v[64:67]
	v_mfma_f32_16x16x32_bf16 v[132:135], v[148:151], v[164:167], v[132:135]
	v_mfma_f32_16x16x32_bf16 v[128:131], v[156:159], v[164:167], v[128:131]
	v_mfma_f32_16x16x32_bf16 v[108:111], v[148:151], v[172:175], v[108:111]
	v_mfma_f32_16x16x32_bf16 v[104:107], v[156:159], v[172:175], v[104:107]
	v_mfma_f32_16x16x32_bf16 v[84:87], v[148:151], v[180:183], v[84:87]
	v_mfma_f32_16x16x32_bf16 v[80:83], v[156:159], v[180:183], v[80:83]
	v_mfma_f32_16x16x32_bf16 v[68:71], v[148:151], v[204:207], v[68:71]
	v_mfma_f32_16x16x32_bf16 v[64:67], v[156:159], v[204:207], v[64:67]
	s_setprio 0
	s_barrier
	s_add_i32 s73, s58, s17
	v_lshl_add_u64 v[208:209], s[40:41], 0, v[186:187]
	s_mov_b32 m0, s73
	ds_read_b128 v[160:163], v217 offset:16384
	ds_read_b128 v[164:167], v217 offset:17408
	ds_read_b128 v[168:171], v217 offset:18432
	ds_read_b128 v[172:175], v217 offset:19456
	ds_read_b128 v[176:179], v217 offset:20480
	ds_read_b128 v[180:183], v217 offset:21504
	ds_read_b128 v[200:203], v217 offset:22528
	ds_read_b128 v[204:207], v217 offset:23552
	global_load_lds_dwordx4 v[208:209], off
	s_add_i32 m0, s73, 0x2000
	s_add_u32 s76, s40, 0x80000
	v_lshl_add_u64 v[210:211], s[40:41], 0, v[190:191]
	s_addc_u32 s77, s41, 0
	s_add_i32 s73, s59, s17
	global_load_lds_dwordx4 v[210:211], off
	v_lshl_add_u64 v[218:219], s[76:77], 0, v[186:187]
	s_mov_b32 m0, s73
	v_lshl_add_u64 v[220:221], s[42:43], 0, v[188:189]
	global_load_lds_dwordx4 v[218:219], off
	v_lshl_add_u64 v[218:219], s[76:77], 0, v[190:191]
	s_add_i32 m0, s73, 0x2000
	s_nop 0
	global_load_lds_dwordx4 v[218:219], off
	v_lshl_add_u64 v[218:219], s[42:43], 0, v[184:185]
	s_mov_b32 m0, s48
	s_nop 0
	global_load_lds_dwordx4 v[218:219], off
	s_mov_b32 m0, s49
	s_nop 0
	global_load_lds_dwordx4 v[220:221], off
	s_waitcnt vmcnt(8)
	s_waitcnt lgkmcnt(0)
	s_barrier
; #define PG8_STAGE(bufoff, gbase, voff) do { _Pragma("unroll") for (int _i = 0; _i < 2; ++_i) \
;         __builtin_amdgcn_global_load_lds((const unsigned*)((const char*)(gbase) + (voff)[_i]), (LAS unsigned*)(lds + (bufoff) + ldsw + _i * 8192), 16, 0, 0); } while (0)
; #define PG8_LDA(dst, b, h) do { _Pragma("unroll") for (int m = 0; m < 4; ++m) _Pragma("unroll") for (int k = 0; k < 2; ++k) dst[m][k] = *(const LAS bf16x8*)(lds + PG8_SA(b, h) + aoff + m * 2048 + k * 1024); } while (0)
; #define PG8_LDB(dst, b, h) do { _Pragma("unroll") for (int n = 0; n < 2; ++n) _Pragma("unroll") for (int k = 0; k < 2; ++k) dst[n][k] = *(const LAS bf16x8*)(lds + PG8_SB(b, h) + boff + n * 2048 + k * 1024); } while (0)
; #define PG8_MMA(ai, bj, At, Bt) do { __builtin_amdgcn_s_setprio(1); _Pragma("unroll") for (int m = 0; m < 4; ++m) _Pragma("unroll") for (int n = 0; n < 2; ++n) _Pragma("unroll") for (int k = 0; k < 2; ++k) \
;         acc[ai][bj][m][n] = __builtin_amdgcn_mfma_f32_16x16x32_bf16(Bt[n][k], At[m][k], acc[ai][bj][m][n], 0, 0, 0); __builtin_amdgcn_s_setprio(0); } while (0)
; #define PG8_WAIT_V(n) asm volatile("s_waitcnt vmcnt(" #n ")" ::: "memory")
; #define PG8_WAIT_L(n) asm volatile("s_waitcnt lgkmcnt(" #n ")" ::: "memory")
; #define PG8_BAR __builtin_amdgcn_s_barrier()
; #define PG8_SCHED __builtin_amdgcn_sched_barrier(0)
; template <class Epi, class Sched = StaticOrder, class EpiSub = NoSub, bool FAST = false>
; __device__ __forceinline__ void gemm_phase(LAS unsigned char* lds, const Gemm g, const Sched& S, const Epi& E, const EpiSub& ES = EpiSub()) {
;     ...
;             PG8_WAIT_V(8); PG8_WAIT_L(0); PG8_BAR; PG8_MMA(1, 0, At, B0); PG8_MMA(1, 1, At, B1); PG8_BAR; PG8_SCHED;
;             PG8_LDB(B0, 1, 0); PG8_LDB(B1, 1, 1); PG8_SCHED; PG8_LDA(At, 1, 0); PG8_STAGE(PG8_SA(0, 1), a2 + hstepA, voffA);
;             PG8_WAIT_V(8); PG8_WAIT_L(0); PG8_BAR; PG8_MMA(0, 0, At, B0); PG8_MMA(0, 1, At, B1); PG8_BAR; PG8_SCHED;
	s_setprio 1
	v_mfma_f32_16x16x32_bf16 v[60:63], v[96:99], v[160:163], v[60:63]
	v_mfma_f32_16x16x32_bf16 v[56:59], v[112:115], v[160:163], v[56:59]
	v_mfma_f32_16x16x32_bf16 v[44:47], v[96:99], v[168:171], v[44:47]
	v_mfma_f32_16x16x32_bf16 v[40:43], v[112:115], v[168:171], v[40:43]
	v_mfma_f32_16x16x32_bf16 v[28:31], v[96:99], v[176:179], v[28:31]
	v_mfma_f32_16x16x32_bf16 v[24:27], v[112:115], v[176:179], v[24:27]
	v_mfma_f32_16x16x32_bf16 v[12:15], v[96:99], v[200:203], v[12:15]
	v_mfma_f32_16x16x32_bf16 v[8:11], v[112:115], v[200:203], v[8:11]
	v_mfma_f32_16x16x32_bf16 v[60:63], v[100:103], v[164:167], v[60:63]
	v_mfma_f32_16x16x32_bf16 v[56:59], v[116:119], v[164:167], v[56:59]
	v_mfma_f32_16x16x32_bf16 v[44:47], v[100:103], v[172:175], v[44:47]
	v_mfma_f32_16x16x32_bf16 v[40:43], v[116:119], v[172:175], v[40:43]
	v_mfma_f32_16x16x32_bf16 v[28:31], v[100:103], v[180:183], v[28:31]
	v_mfma_f32_16x16x32_bf16 v[24:27], v[116:119], v[180:183], v[24:27]
	v_mfma_f32_16x16x32_bf16 v[12:15], v[100:103], v[204:207], v[12:15]
	v_mfma_f32_16x16x32_bf16 v[8:11], v[116:119], v[204:207], v[8:11]
	v_mfma_f32_16x16x32_bf16 v[52:55], v[144:147], v[160:163], v[52:55]
	v_mfma_f32_16x16x32_bf16 v[48:51], v[152:155], v[160:163], v[48:51]
	v_mfma_f32_16x16x32_bf16 v[36:39], v[144:147], v[168:171], v[36:39]
	v_mfma_f32_16x16x32_bf16 v[32:35], v[152:155], v[168:171], v[32:35]
	v_mfma_f32_16x16x32_bf16 v[20:23], v[144:147], v[176:179], v[20:23]
	v_mfma_f32_16x16x32_bf16 v[16:19], v[152:155], v[176:179], v[16:19]
	v_mfma_f32_16x16x32_bf16 v[4:7], v[144:147], v[200:203], v[4:7]
	v_mfma_f32_16x16x32_bf16 v[0:3], v[152:155], v[200:203], v[0:3]
	v_mfma_f32_16x16x32_bf16 v[52:55], v[148:151], v[164:167], v[52:55]
	v_mfma_f32_16x16x32_bf16 v[48:51], v[156:159], v[164:167], v[48:51]
	v_mfma_f32_16x16x32_bf16 v[36:39], v[148:151], v[172:175], v[36:39]
	v_mfma_f32_16x16x32_bf16 v[32:35], v[156:159], v[172:175], v[32:35]
	v_mfma_f32_16x16x32_bf16 v[20:23], v[148:151], v[180:183], v[20:23]
	v_mfma_f32_16x16x32_bf16 v[16:19], v[156:159], v[180:183], v[16:19]
	v_mfma_f32_16x16x32_bf16 v[4:7], v[148:151], v[204:207], v[4:7]
	v_mfma_f32_16x16x32_bf16 v[0:3], v[156:159], v[204:207], v[0:3]
	s_setprio 0
	s_barrier
	s_add_i32 s73, 0, 0x18000
	s_add_i32 s76, 0, 0x1c000
	v_add_u32_e32 v116, s73, v212
	v_add_u32_e32 v156, s76, v212
	ds_read_b128 v[96:99], v116
	ds_read_b128 v[100:103], v116 offset:1024
	ds_read_b128 v[112:115], v116 offset:2048
	ds_read_b128 v[116:119], v116 offset:3072
	ds_read_b128 v[144:147], v156
	ds_read_b128 v[148:151], v156 offset:1024
	ds_read_b128 v[152:155], v156 offset:2048
	ds_read_b128 v[156:159], v156 offset:3072
	s_add_u32 s42, s42, 0x80000
	s_addc_u32 s43, s43, 0
	s_mov_b32 m0, s50
	v_lshl_add_u64 v[222:223], s[42:43], 0, v[184:185]
	ds_read_b128 v[160:163], v217 offset:32768
	ds_read_b128 v[164:167], v217 offset:33792
	ds_read_b128 v[168:171], v217 offset:34816
	ds_read_b128 v[172:175], v217 offset:35840
	ds_read_b128 v[176:179], v217 offset:36864
	ds_read_b128 v[180:183], v217 offset:37888
	ds_read_b128 v[200:203], v217 offset:38912
	ds_read_b128 v[204:207], v217 offset:39936
	global_load_lds_dwordx4 v[222:223], off
	v_lshl_add_u64 v[222:223], s[42:43], 0, v[188:189]
	s_mov_b32 m0, s51
	s_nop 0
	global_load_lds_dwordx4 v[222:223], off
	s_waitcnt vmcnt(8)
	s_waitcnt lgkmcnt(0)
	s_barrier
	s_setprio 1
	v_mfma_f32_16x16x32_bf16 v[140:143], v[96:99], v[160:163], v[140:143]
	v_mfma_f32_16x16x32_bf16 v[136:139], v[112:115], v[160:163], v[136:139]
	v_mfma_f32_16x16x32_bf16 v[124:127], v[96:99], v[168:171], v[124:127]
	v_mfma_f32_16x16x32_bf16 v[120:123], v[112:115], v[168:171], v[120:123]
	v_mfma_f32_16x16x32_bf16 v[92:95], v[96:99], v[176:179], v[92:95]
	v_mfma_f32_16x16x32_bf16 v[88:91], v[112:115], v[176:179], v[88:91]
	v_mfma_f32_16x16x32_bf16 v[76:79], v[96:99], v[200:203], v[76:79]
	v_mfma_f32_16x16x32_bf16 v[72:75], v[112:115], v[200:203], v[72:75]
	v_mfma_f32_16x16x32_bf16 v[140:143], v[100:103], v[164:167], v[140:143]
	v_mfma_f32_16x16x32_bf16 v[136:139], v[116:119], v[164:167], v[136:139]
	v_mfma_f32_16x16x32_bf16 v[124:127], v[100:103], v[172:175], v[124:127]
	v_mfma_f32_16x16x32_bf16 v[120:123], v[116:119], v[172:175], v[120:123]
	v_mfma_f32_16x16x32_bf16 v[92:95], v[100:103], v[180:183], v[92:95]
	v_mfma_f32_16x16x32_bf16 v[88:91], v[116:119], v[180:183], v[88:91]
	v_mfma_f32_16x16x32_bf16 v[76:79], v[100:103], v[204:207], v[76:79]
	v_mfma_f32_16x16x32_bf16 v[72:75], v[116:119], v[204:207], v[72:75]
	v_mfma_f32_16x16x32_bf16 v[132:135], v[144:147], v[160:163], v[132:135]
	v_mfma_f32_16x16x32_bf16 v[128:131], v[152:155], v[160:163], v[128:131]
	v_mfma_f32_16x16x32_bf16 v[108:111], v[144:147], v[168:171], v[108:111]
	v_mfma_f32_16x16x32_bf16 v[104:107], v[152:155], v[168:171], v[104:107]
	v_mfma_f32_16x16x32_bf16 v[84:87], v[144:147], v[176:179], v[84:87]
	v_mfma_f32_16x16x32_bf16 v[80:83], v[152:155], v[176:179], v[80:83]
	v_mfma_f32_16x16x32_bf16 v[68:71], v[144:147], v[200:203], v[68:71]
	v_mfma_f32_16x16x32_bf16 v[64:67], v[152:155], v[200:203], v[64:67]
	v_mfma_f32_16x16x32_bf16 v[132:135], v[148:151], v[164:167], v[132:135]
	v_mfma_f32_16x16x32_bf16 v[128:131], v[156:159], v[164:167], v[128:131]
	v_mfma_f32_16x16x32_bf16 v[108:111], v[148:151], v[172:175], v[108:111]
	v_mfma_f32_16x16x32_bf16 v[104:107], v[156:159], v[172:175], v[104:107]
	v_mfma_f32_16x16x32_bf16 v[84:87], v[148:151], v[180:183], v[84:87]
	v_mfma_f32_16x16x32_bf16 v[80:83], v[156:159], v[180:183], v[80:83]
	v_mfma_f32_16x16x32_bf16 v[68:71], v[148:151], v[204:207], v[68:71]
	v_mfma_f32_16x16x32_bf16 v[64:67], v[156:159], v[204:207], v[64:67]
	s_setprio 0
	s_barrier
; #define PG8_STAGE(bufoff, gbase, voff) do { _Pragma("unroll") for (int _i = 0; _i < 2; ++_i) \
;         __builtin_amdgcn_global_load_lds((const unsigned*)((const char*)(gbase) + (voff)[_i]), (LAS unsigned*)(lds + (bufoff) + ldsw + _i * 8192), 16, 0, 0); } while (0)
; #define PG8_LDA(dst, b, h) do { _Pragma("unroll") for (int m = 0; m < 4; ++m) _Pragma("unroll") for (int k = 0; k < 2; ++k) dst[m][k] = *(const LAS bf16x8*)(lds + PG8_SA(b, h) + aoff + m * 2048 + k * 1024); } while (0)
; #define PG8_MMA(ai, bj, At, Bt) do { __builtin_amdgcn_s_setprio(1); _Pragma("unroll") for (int m = 0; m < 4; ++m) _Pragma("unroll") for (int n = 0; n < 2; ++n) _Pragma("unroll") for (int k = 0; k < 2; ++k) \
;         acc[ai][bj][m][n] = __builtin_amdgcn_mfma_f32_16x16x32_bf16(Bt[n][k], At[m][k], acc[ai][bj][m][n], 0, 0, 0); __builtin_amdgcn_s_setprio(0); } while (0)
; #define PG8_WAIT_V(n) asm volatile("s_waitcnt vmcnt(" #n ")" ::: "memory")
; #define PG8_WAIT_L(n) asm volatile("s_waitcnt lgkmcnt(" #n ")" ::: "memory")
; #define PG8_BAR __builtin_amdgcn_s_barrier()
; #define PG8_SCHED __builtin_amdgcn_sched_barrier(0)
; template <class Epi, class Sched = StaticOrder, class EpiSub = NoSub, bool FAST = false>
; __device__ __forceinline__ void gemm_phase(LAS unsigned char* lds, const Gemm g, const Sched& S, const Epi& E, const EpiSub& ES = EpiSub()) {
;     ...
;             PG8_LDA(At, 1, 1); PG8_STAGE(PG8_SB(1, 0), b3, voffB); PG8_STAGE(PG8_SB(1, 1), b3 + hstepB, voffB); PG8_STAGE(PG8_SA(1, 0), a3, voffA);
;             PG8_WAIT_V(8); PG8_WAIT_L(0); PG8_BAR; PG8_MMA(1, 0, At, B0); PG8_MMA(1, 1, At, B1); PG8_BAR; PG8_SCHED;
;     ...
;         if constexpr (FAST && PG8_ALIGN) { if (wr == 0) PG8_BAR; }
	s_add_i32 s42, s73, s17
	v_lshl_add_u64 v[208:209], v[208:209], 0, s[12:13]
	s_mov_b32 m0, s42
	ds_read_b128 v[160:163], v217 offset:49152
	ds_read_b128 v[164:167], v217 offset:50176
	ds_read_b128 v[168:171], v217 offset:51200
	ds_read_b128 v[172:175], v217 offset:52224
	ds_read_b128 v[176:179], v217 offset:53248
	ds_read_b128 v[180:183], v217 offset:54272
	ds_read_b128 v[200:203], v217 offset:55296
	ds_read_b128 v[204:207], v217 offset:56320
	global_load_lds_dwordx4 v[208:209], off
	s_add_i32 m0, s42, 0x2000
	s_add_u32 s40, s40, 0x80080
	v_lshl_add_u64 v[208:209], v[210:211], 0, s[12:13]
	s_addc_u32 s41, s41, 0
	s_add_i32 s42, s76, s17
	global_load_lds_dwordx4 v[208:209], off
	v_lshl_add_u64 v[208:209], s[40:41], 0, v[186:187]
	s_mov_b32 m0, s42
	s_nop 0
	global_load_lds_dwordx4 v[208:209], off
	v_lshl_add_u64 v[208:209], s[40:41], 0, v[190:191]
	s_add_i32 m0, s42, 0x2000
	s_nop 0
	global_load_lds_dwordx4 v[208:209], off
	v_lshl_add_u64 v[208:209], v[218:219], 0, s[12:13]
	s_mov_b32 m0, s55
	s_nop 0
	global_load_lds_dwordx4 v[208:209], off
	v_lshl_add_u64 v[208:209], v[220:221], 0, s[12:13]
	s_mov_b32 m0, s56
	s_nop 0
	global_load_lds_dwordx4 v[208:209], off
	s_waitcnt vmcnt(8)
	s_waitcnt lgkmcnt(0)
	s_barrier
	s_setprio 1
	v_mfma_f32_16x16x32_bf16 v[60:63], v[96:99], v[160:163], v[60:63]
	v_mfma_f32_16x16x32_bf16 v[56:59], v[112:115], v[160:163], v[56:59]
	v_mfma_f32_16x16x32_bf16 v[44:47], v[96:99], v[168:171], v[44:47]
	v_mfma_f32_16x16x32_bf16 v[40:43], v[112:115], v[168:171], v[40:43]
	v_mfma_f32_16x16x32_bf16 v[28:31], v[96:99], v[176:179], v[28:31]
	v_mfma_f32_16x16x32_bf16 v[24:27], v[112:115], v[176:179], v[24:27]
	v_mfma_f32_16x16x32_bf16 v[12:15], v[96:99], v[200:203], v[12:15]
	v_mfma_f32_16x16x32_bf16 v[8:11], v[112:115], v[200:203], v[8:11]
	v_mfma_f32_16x16x32_bf16 v[60:63], v[100:103], v[164:167], v[60:63]
	v_mfma_f32_16x16x32_bf16 v[56:59], v[116:119], v[164:167], v[56:59]
	v_mfma_f32_16x16x32_bf16 v[44:47], v[100:103], v[172:175], v[44:47]
	v_mfma_f32_16x16x32_bf16 v[40:43], v[116:119], v[172:175], v[40:43]
	v_mfma_f32_16x16x32_bf16 v[28:31], v[100:103], v[180:183], v[28:31]
	v_mfma_f32_16x16x32_bf16 v[24:27], v[116:119], v[180:183], v[24:27]
	v_mfma_f32_16x16x32_bf16 v[12:15], v[100:103], v[204:207], v[12:15]
	v_mfma_f32_16x16x32_bf16 v[8:11], v[116:119], v[204:207], v[8:11]
	v_mfma_f32_16x16x32_bf16 v[52:55], v[144:147], v[160:163], v[52:55]
	v_mfma_f32_16x16x32_bf16 v[48:51], v[152:155], v[160:163], v[48:51]
	v_mfma_f32_16x16x32_bf16 v[36:39], v[144:147], v[168:171], v[36:39]
	v_mfma_f32_16x16x32_bf16 v[32:35], v[152:155], v[168:171], v[32:35]
	v_mfma_f32_16x16x32_bf16 v[20:23], v[144:147], v[176:179], v[20:23]
	v_mfma_f32_16x16x32_bf16 v[16:19], v[152:155], v[176:179], v[16:19]
	v_mfma_f32_16x16x32_bf16 v[4:7], v[144:147], v[200:203], v[4:7]
	v_mfma_f32_16x16x32_bf16 v[0:3], v[152:155], v[200:203], v[0:3]
	v_mfma_f32_16x16x32_bf16 v[52:55], v[148:151], v[164:167], v[52:55]
	v_mfma_f32_16x16x32_bf16 v[48:51], v[156:159], v[164:167], v[48:51]
	v_mfma_f32_16x16x32_bf16 v[36:39], v[148:151], v[172:175], v[36:39]
	v_mfma_f32_16x16x32_bf16 v[32:35], v[156:159], v[172:175], v[32:35]
	v_mfma_f32_16x16x32_bf16 v[20:23], v[148:151], v[180:183], v[20:23]
	v_mfma_f32_16x16x32_bf16 v[16:19], v[156:159], v[180:183], v[16:19]
	v_mfma_f32_16x16x32_bf16 v[4:7], v[148:151], v[204:207], v[4:7]
	v_mfma_f32_16x16x32_bf16 v[0:3], v[156:159], v[204:207], v[0:3]
	s_setprio 0
	s_barrier
	s_add_u32 s38, s38, 0x100
	s_addc_u32 s39, s39, 0
	s_add_u32 s70, s70, 0x100
	s_addc_u32 s71, s71, 0
	s_cmp_ge_u32 s72, s29
	s_mov_b32 s42, s72
	s_cbranch_scc0 .LBB0_769
	s_and_b64 vcc, exec, s[14:15]
	s_cbranch_vccz .LBB0_772
	s_barrier

; #define PG8_STAGE(bufoff, gbase, voff) do { _Pragma("unroll") for (int _i = 0; _i < 2; ++_i) \
;         __builtin_amdgcn_global_load_lds((const unsigned*)((const char*)(gbase) + (voff)[_i]), (LAS unsigned*)(lds + (bufoff) + ldsw + _i * 8192), 16, 0, 0); } while (0)
; #define PG8_LDA(dst, b, h) do { _Pragma("unroll") for (int m = 0; m < 4; ++m) _Pragma("unroll") for (int k = 0; k < 2; ++k) dst[m][k] = *(const LAS bf16x8*)(lds + PG8_SA(b, h) + aoff + m * 2048 + k * 1024); } while (0)
; #define PG8_LDB(dst, b, h) do { _Pragma("unroll") for (int n = 0; n < 2; ++n) _Pragma("unroll") for (int k = 0; k < 2; ++k) dst[n][k] = *(const LAS bf16x8*)(lds + PG8_SB(b, h) + boff + n * 2048 + k * 1024); } while (0)
; #define PG8_MMA(ai, bj, At, Bt) do { __builtin_amdgcn_s_setprio(1); _Pragma("unroll") for (int m = 0; m < 4; ++m) _Pragma("unroll") for (int n = 0; n < 2; ++n) _Pragma("unroll") for (int k = 0; k < 2; ++k) \
;         acc[ai][bj][m][n] = __builtin_amdgcn_mfma_f32_16x16x32_bf16(Bt[n][k], At[m][k], acc[ai][bj][m][n], 0, 0, 0); __builtin_amdgcn_s_setprio(0); } while (0)
; #define PG8_WAIT_V(n) asm volatile("s_waitcnt vmcnt(" #n ")" ::: "memory")
; #define PG8_WAIT_L(n) asm volatile("s_waitcnt lgkmcnt(" #n ")" ::: "memory")
; #define PG8_BAR __builtin_amdgcn_s_barrier()
; template <class Epi, class Sched = StaticOrder, class EpiSub = NoSub, bool FAST = false>
; __device__ __forceinline__ void gemm_phase(LAS unsigned char* lds, const Gemm g, const Sched& S, const Epi& E, const EpiSub& ES = EpiSub()) {
;     ...
;             const bool last = (t == nt - 2);
;             const char* a1 = cA + (size_t)(t + 1) * kstep;
;             const char* a2 = last ? nA : cA + (size_t)(t + 2) * kstep; const char* b2 = last ? nB : cB + (size_t)(t + 2) * kstep;
;             const char* a3 = a2 + kstep; const char* b3 = b2 + kstep;
;             if constexpr (FAST && PG8_SP2) {
;             PG8_LDB(B0, 0, 0); PG8_LDB(B1, 0, 1); PG8_SCHED; PG8_LDA(At, 0, 0); PG8_STAGE(PG8_SA(1, 1), a1 + hstepA, voffA);
;             PG8_WAIT_V(8); PG8_WAIT_L(0); PG8_BAR; PG8_MMA(0, 0, At, B0); PG8_MMA(0, 1, At, B1); PG8_BAR; PG8_SCHED;
;             PG8_LDA(At, 0, 1); PG8_STAGE(PG8_SB(0, 0), b2, voffB); PG8_STAGE(PG8_SB(0, 1), b2 + hstepB, voffB); PG8_STAGE(PG8_SA(0, 0), a2, voffA);
;             PG8_WAIT_V(8); PG8_WAIT_L(0); PG8_BAR; PG8_MMA(1, 0, At, B0); PG8_MMA(1, 1, At, B1); PG8_BAR; PG8_SCHED;
.LBB0_985:
	ds_read_b128 v[150:153], v147
	ds_read_b128 v[154:157], v147 offset:1024
	ds_read_b128 v[158:161], v147 offset:2048
	ds_read_b128 v[162:165], v147 offset:3072
	ds_read_b128 v[166:169], v148
	ds_read_b128 v[170:173], v148 offset:1024
	ds_read_b128 v[174:177], v148 offset:2048
	ds_read_b128 v[178:181], v148 offset:3072
	s_add_u32 s24, s22, 0xfff80080
	s_addc_u32 s25, s23, -1
	s_cmp_eq_u32 s49, 28
	s_cselect_b32 s27, s15, s25
	s_cselect_b32 s26, s45, s24
	s_cselect_b32 s25, s13, s48
	s_cselect_b32 s24, s46, s47
	v_lshl_add_u64 v[190:191], s[22:23], 0, v[136:137]
	s_add_i32 m0, s21, 0xc000
	ds_read_b128 v[182:185], v149
	ds_read_b128 v[186:189], v149 offset:1024
	ds_read_b128 v[194:197], v149 offset:2048
	ds_read_b128 v[198:201], v149 offset:3072
	ds_read_b128 v[202:205], v149 offset:4096
	ds_read_b128 v[206:209], v149 offset:5120
	ds_read_b128 v[210:213], v149 offset:6144
	ds_read_b128 v[214:217], v149 offset:7168
	global_load_lds_dwordx4 v[190:191], off
	v_lshl_add_u64 v[190:191], s[22:23], 0, v[138:139]
	s_add_i32 m0, s21, 0xe000
	s_nop 0
	global_load_lds_dwordx4 v[190:191], off
	s_waitcnt vmcnt(8)
	s_waitcnt lgkmcnt(0)
	s_barrier
	s_setprio 1
	v_mfma_f32_16x16x32_bf16 v[124:127], v[150:153], v[182:185], v[124:127]
	v_mfma_f32_16x16x32_bf16 v[116:119], v[158:161], v[182:185], v[116:119]
	v_mfma_f32_16x16x32_bf16 v[108:111], v[150:153], v[194:197], v[108:111]
	v_mfma_f32_16x16x32_bf16 v[100:103], v[158:161], v[194:197], v[100:103]
	v_mfma_f32_16x16x32_bf16 v[92:95], v[150:153], v[202:205], v[92:95]
	v_mfma_f32_16x16x32_bf16 v[84:87], v[158:161], v[202:205], v[84:87]
	v_mfma_f32_16x16x32_bf16 v[76:79], v[150:153], v[210:213], v[76:79]
	v_mfma_f32_16x16x32_bf16 v[68:71], v[158:161], v[210:213], v[68:71]
	v_mfma_f32_16x16x32_bf16 v[124:127], v[154:157], v[186:189], v[124:127]
	v_mfma_f32_16x16x32_bf16 v[116:119], v[162:165], v[186:189], v[116:119]
	v_mfma_f32_16x16x32_bf16 v[108:111], v[154:157], v[198:201], v[108:111]
	v_mfma_f32_16x16x32_bf16 v[100:103], v[162:165], v[198:201], v[100:103]
	v_mfma_f32_16x16x32_bf16 v[92:95], v[154:157], v[206:209], v[92:95]
	v_mfma_f32_16x16x32_bf16 v[84:87], v[162:165], v[206:209], v[84:87]
	v_mfma_f32_16x16x32_bf16 v[76:79], v[154:157], v[214:217], v[76:79]
	v_mfma_f32_16x16x32_bf16 v[68:71], v[162:165], v[214:217], v[68:71]
	v_mfma_f32_16x16x32_bf16 v[120:123], v[166:169], v[182:185], v[120:123]
	v_mfma_f32_16x16x32_bf16 v[112:115], v[174:177], v[182:185], v[112:115]
	v_mfma_f32_16x16x32_bf16 v[104:107], v[166:169], v[194:197], v[104:107]
	v_mfma_f32_16x16x32_bf16 v[96:99], v[174:177], v[194:197], v[96:99]
	v_mfma_f32_16x16x32_bf16 v[88:91], v[166:169], v[202:205], v[88:91]
	v_mfma_f32_16x16x32_bf16 v[80:83], v[174:177], v[202:205], v[80:83]
	v_mfma_f32_16x16x32_bf16 v[72:75], v[166:169], v[210:213], v[72:75]
	v_mfma_f32_16x16x32_bf16 v[64:67], v[174:177], v[210:213], v[64:67]
	v_mfma_f32_16x16x32_bf16 v[120:123], v[170:173], v[186:189], v[120:123]
	v_mfma_f32_16x16x32_bf16 v[112:115], v[178:181], v[186:189], v[112:115]
	v_mfma_f32_16x16x32_bf16 v[104:107], v[170:173], v[198:201], v[104:107]
	v_mfma_f32_16x16x32_bf16 v[96:99], v[178:181], v[198:201], v[96:99]
	v_mfma_f32_16x16x32_bf16 v[88:91], v[170:173], v[206:209], v[88:91]
	v_mfma_f32_16x16x32_bf16 v[80:83], v[178:181], v[206:209], v[80:83]
	v_mfma_f32_16x16x32_bf16 v[72:75], v[170:173], v[214:217], v[72:75]
	v_mfma_f32_16x16x32_bf16 v[64:67], v[178:181], v[214:217], v[64:67]
	s_setprio 0
	s_barrier
	s_add_i32 s50, s42, s28
	v_lshl_add_u64 v[190:191], s[24:25], 0, v[130:131]
	s_mov_b32 m0, s50
	ds_read_b128 v[182:185], v149 offset:16384
	ds_read_b128 v[186:189], v149 offset:17408
	ds_read_b128 v[194:197], v149 offset:18432
	ds_read_b128 v[198:201], v149 offset:19456
	ds_read_b128 v[202:205], v149 offset:20480
	ds_read_b128 v[206:209], v149 offset:21504
	ds_read_b128 v[210:213], v149 offset:22528
	ds_read_b128 v[214:217], v149 offset:23552
	global_load_lds_dwordx4 v[190:191], off
	s_add_i32 m0, s50, 0x2000
	s_add_u32 s50, s24, 0x80000
	v_lshl_add_u64 v[218:219], s[24:25], 0, v[134:135]
	s_addc_u32 s51, s25, 0
	s_add_i32 s52, s43, s28
	global_load_lds_dwordx4 v[218:219], off
	v_lshl_add_u64 v[220:221], s[50:51], 0, v[130:131]
	s_mov_b32 m0, s52
	v_lshl_add_u64 v[222:223], s[26:27], 0, v[132:133]
	global_load_lds_dwordx4 v[220:221], off
	v_lshl_add_u64 v[220:221], s[50:51], 0, v[134:135]
	s_add_i32 m0, s52, 0x2000
	s_nop 0
	global_load_lds_dwordx4 v[220:221], off
	v_lshl_add_u64 v[220:221], s[26:27], 0, v[128:129]
	s_mov_b32 m0, s21
	s_nop 0
	global_load_lds_dwordx4 v[220:221], off
	s_mov_b32 m0, s31
	s_nop 0
	global_load_lds_dwordx4 v[222:223], off
	s_waitcnt vmcnt(8)
	s_waitcnt lgkmcnt(0)
	s_barrier
; #define PG8_STAGE(bufoff, gbase, voff) do { _Pragma("unroll") for (int _i = 0; _i < 2; ++_i) \
;         __builtin_amdgcn_global_load_lds((const unsigned*)((const char*)(gbase) + (voff)[_i]), (LAS unsigned*)(lds + (bufoff) + ldsw + _i * 8192), 16, 0, 0); } while (0)
; #define PG8_LDA(dst, b, h) do { _Pragma("unroll") for (int m = 0; m < 4; ++m) _Pragma("unroll") for (int k = 0; k < 2; ++k) dst[m][k] = *(const LAS bf16x8*)(lds + PG8_SA(b, h) + aoff + m * 2048 + k * 1024); } while (0)
; #define PG8_LDB(dst, b, h) do { _Pragma("unroll") for (int n = 0; n < 2; ++n) _Pragma("unroll") for (int k = 0; k < 2; ++k) dst[n][k] = *(const LAS bf16x8*)(lds + PG8_SB(b, h) + boff + n * 2048 + k * 1024); } while (0)
; #define PG8_MMA(ai, bj, At, Bt) do { __builtin_amdgcn_s_setprio(1); _Pragma("unroll") for (int m = 0; m < 4; ++m) _Pragma("unroll") for (int n = 0; n < 2; ++n) _Pragma("unroll") for (int k = 0; k < 2; ++k) \
;         acc[ai][bj][m][n] = __builtin_amdgcn_mfma_f32_16x16x32_bf16(Bt[n][k], At[m][k], acc[ai][bj][m][n], 0, 0, 0); __builtin_amdgcn_s_setprio(0); } while (0)
; #define PG8_WAIT_V(n) asm volatile("s_waitcnt vmcnt(" #n ")" ::: "memory")
; #define PG8_WAIT_L(n) asm volatile("s_waitcnt lgkmcnt(" #n ")" ::: "memory")
; #define PG8_BAR __builtin_amdgcn_s_barrier()
; #define PG8_SCHED __builtin_amdgcn_sched_barrier(0)
; template <class Epi, class Sched = StaticOrder, class EpiSub = NoSub, bool FAST = false>
; __device__ __forceinline__ void gemm_phase(LAS unsigned char* lds, const Gemm g, const Sched& S, const Epi& E, const EpiSub& ES = EpiSub()) {
;     ...
;             PG8_WAIT_V(8); PG8_WAIT_L(0); PG8_BAR; PG8_MMA(1, 0, At, B0); PG8_MMA(1, 1, At, B1); PG8_BAR; PG8_SCHED;
;             PG8_LDB(B0, 1, 0); PG8_LDB(B1, 1, 1); PG8_SCHED; PG8_LDA(At, 1, 0); PG8_STAGE(PG8_SA(0, 1), a2 + hstepA, voffA);
;             PG8_WAIT_V(8); PG8_WAIT_L(0); PG8_BAR; PG8_MMA(0, 0, At, B0); PG8_MMA(0, 1, At, B1); PG8_BAR; PG8_SCHED;
	s_setprio 1
	v_mfma_f32_16x16x32_bf16 v[60:63], v[150:153], v[182:185], v[60:63]
	v_mfma_f32_16x16x32_bf16 v[52:55], v[158:161], v[182:185], v[52:55]
	v_mfma_f32_16x16x32_bf16 v[44:47], v[150:153], v[194:197], v[44:47]
	v_mfma_f32_16x16x32_bf16 v[36:39], v[158:161], v[194:197], v[36:39]
	v_mfma_f32_16x16x32_bf16 v[28:31], v[150:153], v[202:205], v[28:31]
	v_mfma_f32_16x16x32_bf16 v[20:23], v[158:161], v[202:205], v[20:23]
	v_mfma_f32_16x16x32_bf16 v[12:15], v[150:153], v[210:213], v[12:15]
	v_mfma_f32_16x16x32_bf16 v[4:7], v[158:161], v[210:213], v[4:7]
	v_mfma_f32_16x16x32_bf16 v[60:63], v[154:157], v[186:189], v[60:63]
	v_mfma_f32_16x16x32_bf16 v[52:55], v[162:165], v[186:189], v[52:55]
	v_mfma_f32_16x16x32_bf16 v[44:47], v[154:157], v[198:201], v[44:47]
	v_mfma_f32_16x16x32_bf16 v[36:39], v[162:165], v[198:201], v[36:39]
	v_mfma_f32_16x16x32_bf16 v[28:31], v[154:157], v[206:209], v[28:31]
	v_mfma_f32_16x16x32_bf16 v[20:23], v[162:165], v[206:209], v[20:23]
	v_mfma_f32_16x16x32_bf16 v[12:15], v[154:157], v[214:217], v[12:15]
	v_mfma_f32_16x16x32_bf16 v[4:7], v[162:165], v[214:217], v[4:7]
	v_mfma_f32_16x16x32_bf16 v[56:59], v[166:169], v[182:185], v[56:59]
	v_mfma_f32_16x16x32_bf16 v[48:51], v[174:177], v[182:185], v[48:51]
	v_mfma_f32_16x16x32_bf16 v[40:43], v[166:169], v[194:197], v[40:43]
	v_mfma_f32_16x16x32_bf16 v[32:35], v[174:177], v[194:197], v[32:35]
	v_mfma_f32_16x16x32_bf16 v[24:27], v[166:169], v[202:205], v[24:27]
	v_mfma_f32_16x16x32_bf16 v[16:19], v[174:177], v[202:205], v[16:19]
	v_mfma_f32_16x16x32_bf16 v[8:11], v[166:169], v[210:213], v[8:11]
	v_mfma_f32_16x16x32_bf16 v[0:3], v[174:177], v[210:213], v[0:3]
	v_mfma_f32_16x16x32_bf16 v[56:59], v[170:173], v[186:189], v[56:59]
	v_mfma_f32_16x16x32_bf16 v[48:51], v[178:181], v[186:189], v[48:51]
	v_mfma_f32_16x16x32_bf16 v[40:43], v[170:173], v[198:201], v[40:43]
	v_mfma_f32_16x16x32_bf16 v[32:35], v[178:181], v[198:201], v[32:35]
	v_mfma_f32_16x16x32_bf16 v[24:27], v[170:173], v[206:209], v[24:27]
	v_mfma_f32_16x16x32_bf16 v[16:19], v[178:181], v[206:209], v[16:19]
	v_mfma_f32_16x16x32_bf16 v[8:11], v[170:173], v[214:217], v[8:11]
	v_mfma_f32_16x16x32_bf16 v[0:3], v[178:181], v[214:217], v[0:3]
	s_setprio 0
	s_barrier
	s_add_i32 s50, 0, 0x18000
	s_add_i32 s51, 0, 0x1c000
	v_add_u32_e32 v162, s50, v145
	v_add_u32_e32 v178, s51, v145
	ds_read_b128 v[150:153], v162
	ds_read_b128 v[154:157], v162 offset:1024
	ds_read_b128 v[158:161], v162 offset:2048
	ds_read_b128 v[162:165], v162 offset:3072
	ds_read_b128 v[166:169], v178
	ds_read_b128 v[170:173], v178 offset:1024
	ds_read_b128 v[174:177], v178 offset:2048
	ds_read_b128 v[178:181], v178 offset:3072
	s_add_u32 s26, s26, 0x80000
	s_addc_u32 s27, s27, 0
	s_mov_b32 m0, s36
	v_lshl_add_u64 v[224:225], s[26:27], 0, v[128:129]
	ds_read_b128 v[182:185], v149 offset:32768
	ds_read_b128 v[186:189], v149 offset:33792
	ds_read_b128 v[194:197], v149 offset:34816
	ds_read_b128 v[198:201], v149 offset:35840
	ds_read_b128 v[202:205], v149 offset:36864
	ds_read_b128 v[206:209], v149 offset:37888
	ds_read_b128 v[210:213], v149 offset:38912
	ds_read_b128 v[214:217], v149 offset:39936
	global_load_lds_dwordx4 v[224:225], off
	v_lshl_add_u64 v[224:225], s[26:27], 0, v[132:133]
	s_mov_b32 m0, s37
	s_nop 0
	global_load_lds_dwordx4 v[224:225], off
	s_waitcnt vmcnt(8)
	s_waitcnt lgkmcnt(0)
	s_barrier
	s_setprio 1
	v_mfma_f32_16x16x32_bf16 v[124:127], v[150:153], v[182:185], v[124:127]
	v_mfma_f32_16x16x32_bf16 v[116:119], v[158:161], v[182:185], v[116:119]
	v_mfma_f32_16x16x32_bf16 v[108:111], v[150:153], v[194:197], v[108:111]
	v_mfma_f32_16x16x32_bf16 v[100:103], v[158:161], v[194:197], v[100:103]
	v_mfma_f32_16x16x32_bf16 v[92:95], v[150:153], v[202:205], v[92:95]
	v_mfma_f32_16x16x32_bf16 v[84:87], v[158:161], v[202:205], v[84:87]
	v_mfma_f32_16x16x32_bf16 v[76:79], v[150:153], v[210:213], v[76:79]
	v_mfma_f32_16x16x32_bf16 v[68:71], v[158:161], v[210:213], v[68:71]
	v_mfma_f32_16x16x32_bf16 v[124:127], v[154:157], v[186:189], v[124:127]
	v_mfma_f32_16x16x32_bf16 v[116:119], v[162:165], v[186:189], v[116:119]
	v_mfma_f32_16x16x32_bf16 v[108:111], v[154:157], v[198:201], v[108:111]
	v_mfma_f32_16x16x32_bf16 v[100:103], v[162:165], v[198:201], v[100:103]
	v_mfma_f32_16x16x32_bf16 v[92:95], v[154:157], v[206:209], v[92:95]
	v_mfma_f32_16x16x32_bf16 v[84:87], v[162:165], v[206:209], v[84:87]
	v_mfma_f32_16x16x32_bf16 v[76:79], v[154:157], v[214:217], v[76:79]
	v_mfma_f32_16x16x32_bf16 v[68:71], v[162:165], v[214:217], v[68:71]
	v_mfma_f32_16x16x32_bf16 v[120:123], v[166:169], v[182:185], v[120:123]
	v_mfma_f32_16x16x32_bf16 v[112:115], v[174:177], v[182:185], v[112:115]
	v_mfma_f32_16x16x32_bf16 v[104:107], v[166:169], v[194:197], v[104:107]
	v_mfma_f32_16x16x32_bf16 v[96:99], v[174:177], v[194:197], v[96:99]
	v_mfma_f32_16x16x32_bf16 v[88:91], v[166:169], v[202:205], v[88:91]
	v_mfma_f32_16x16x32_bf16 v[80:83], v[174:177], v[202:205], v[80:83]
	v_mfma_f32_16x16x32_bf16 v[72:75], v[166:169], v[210:213], v[72:75]
	v_mfma_f32_16x16x32_bf16 v[64:67], v[174:177], v[210:213], v[64:67]
	v_mfma_f32_16x16x32_bf16 v[120:123], v[170:173], v[186:189], v[120:123]
	v_mfma_f32_16x16x32_bf16 v[112:115], v[178:181], v[186:189], v[112:115]
	v_mfma_f32_16x16x32_bf16 v[104:107], v[170:173], v[198:201], v[104:107]
	v_mfma_f32_16x16x32_bf16 v[96:99], v[178:181], v[198:201], v[96:99]
	v_mfma_f32_16x16x32_bf16 v[88:91], v[170:173], v[206:209], v[88:91]
	v_mfma_f32_16x16x32_bf16 v[80:83], v[178:181], v[206:209], v[80:83]
	v_mfma_f32_16x16x32_bf16 v[72:75], v[170:173], v[214:217], v[72:75]
	v_mfma_f32_16x16x32_bf16 v[64:67], v[178:181], v[214:217], v[64:67]
	s_setprio 0
	s_barrier
; #define PG8_STAGE(bufoff, gbase, voff) do { _Pragma("unroll") for (int _i = 0; _i < 2; ++_i) \
;         __builtin_amdgcn_global_load_lds((const unsigned*)((const char*)(gbase) + (voff)[_i]), (LAS unsigned*)(lds + (bufoff) + ldsw + _i * 8192), 16, 0, 0); } while (0)
; #define PG8_LDA(dst, b, h) do { _Pragma("unroll") for (int m = 0; m < 4; ++m) _Pragma("unroll") for (int k = 0; k < 2; ++k) dst[m][k] = *(const LAS bf16x8*)(lds + PG8_SA(b, h) + aoff + m * 2048 + k * 1024); } while (0)
; #define PG8_MMA(ai, bj, At, Bt) do { __builtin_amdgcn_s_setprio(1); _Pragma("unroll") for (int m = 0; m < 4; ++m) _Pragma("unroll") for (int n = 0; n < 2; ++n) _Pragma("unroll") for (int k = 0; k < 2; ++k) \
;         acc[ai][bj][m][n] = __builtin_amdgcn_mfma_f32_16x16x32_bf16(Bt[n][k], At[m][k], acc[ai][bj][m][n], 0, 0, 0); __builtin_amdgcn_s_setprio(0); } while (0)
; #define PG8_WAIT_V(n) asm volatile("s_waitcnt vmcnt(" #n ")" ::: "memory")
; #define PG8_WAIT_L(n) asm volatile("s_waitcnt lgkmcnt(" #n ")" ::: "memory")
; #define PG8_BAR __builtin_amdgcn_s_barrier()
; #define PG8_SCHED __builtin_amdgcn_sched_barrier(0)
; template <class Epi, class Sched = StaticOrder, class EpiSub = NoSub, bool FAST = false>
; __device__ __forceinline__ void gemm_phase(LAS unsigned char* lds, const Gemm g, const Sched& S, const Epi& E, const EpiSub& ES = EpiSub()) {
;     ...
;         for (int t = 0; t < nt; t += 2) {
;     ...
;             PG8_LDA(At, 1, 1); PG8_STAGE(PG8_SB(1, 0), b3, voffB); PG8_STAGE(PG8_SB(1, 1), b3 + hstepB, voffB); PG8_STAGE(PG8_SA(1, 0), a3, voffA);
;             PG8_WAIT_V(8); PG8_WAIT_L(0); PG8_BAR; PG8_MMA(1, 0, At, B0); PG8_MMA(1, 1, At, B1); PG8_BAR; PG8_SCHED;
	s_add_i32 s26, s50, s28
	v_lshl_add_u64 v[190:191], v[190:191], 0, s[8:9]
	s_mov_b32 m0, s26
	ds_read_b128 v[182:185], v149 offset:49152
	ds_read_b128 v[186:189], v149 offset:50176
	ds_read_b128 v[194:197], v149 offset:51200
	ds_read_b128 v[198:201], v149 offset:52224
	ds_read_b128 v[202:205], v149 offset:53248
	ds_read_b128 v[206:209], v149 offset:54272
	ds_read_b128 v[210:213], v149 offset:55296
	ds_read_b128 v[214:217], v149 offset:56320
	global_load_lds_dwordx4 v[190:191], off
	s_add_i32 m0, s26, 0x2000
	s_add_u32 s24, s24, 0x80080
	v_lshl_add_u64 v[190:191], v[218:219], 0, s[8:9]
	s_addc_u32 s25, s25, 0
	s_add_i32 s26, s51, s28
	global_load_lds_dwordx4 v[190:191], off
	v_lshl_add_u64 v[190:191], s[24:25], 0, v[130:131]
	s_mov_b32 m0, s26
	s_nop 0
	global_load_lds_dwordx4 v[190:191], off
	v_lshl_add_u64 v[190:191], s[24:25], 0, v[134:135]
	s_add_i32 m0, s26, 0x2000
	s_nop 0
	global_load_lds_dwordx4 v[190:191], off
	v_lshl_add_u64 v[190:191], v[220:221], 0, s[8:9]
	s_mov_b32 m0, s40
	s_nop 0
	global_load_lds_dwordx4 v[190:191], off
	v_lshl_add_u64 v[190:191], v[222:223], 0, s[8:9]
	s_mov_b32 m0, s41
	s_nop 0
	global_load_lds_dwordx4 v[190:191], off
	s_waitcnt vmcnt(8)
	s_waitcnt lgkmcnt(0)
	s_barrier
	s_setprio 1
	v_mfma_f32_16x16x32_bf16 v[60:63], v[150:153], v[182:185], v[60:63]
	v_mfma_f32_16x16x32_bf16 v[52:55], v[158:161], v[182:185], v[52:55]
	v_mfma_f32_16x16x32_bf16 v[44:47], v[150:153], v[194:197], v[44:47]
	v_mfma_f32_16x16x32_bf16 v[36:39], v[158:161], v[194:197], v[36:39]
	v_mfma_f32_16x16x32_bf16 v[28:31], v[150:153], v[202:205], v[28:31]
	v_mfma_f32_16x16x32_bf16 v[20:23], v[158:161], v[202:205], v[20:23]
	v_mfma_f32_16x16x32_bf16 v[12:15], v[150:153], v[210:213], v[12:15]
	v_mfma_f32_16x16x32_bf16 v[4:7], v[158:161], v[210:213], v[4:7]
	v_mfma_f32_16x16x32_bf16 v[60:63], v[154:157], v[186:189], v[60:63]
	v_mfma_f32_16x16x32_bf16 v[52:55], v[162:165], v[186:189], v[52:55]
	v_mfma_f32_16x16x32_bf16 v[44:47], v[154:157], v[198:201], v[44:47]
	v_mfma_f32_16x16x32_bf16 v[36:39], v[162:165], v[198:201], v[36:39]
	v_mfma_f32_16x16x32_bf16 v[28:31], v[154:157], v[206:209], v[28:31]
	v_mfma_f32_16x16x32_bf16 v[20:23], v[162:165], v[206:209], v[20:23]
	v_mfma_f32_16x16x32_bf16 v[12:15], v[154:157], v[214:217], v[12:15]
	v_mfma_f32_16x16x32_bf16 v[4:7], v[162:165], v[214:217], v[4:7]
	v_mfma_f32_16x16x32_bf16 v[56:59], v[166:169], v[182:185], v[56:59]
	v_mfma_f32_16x16x32_bf16 v[48:51], v[174:177], v[182:185], v[48:51]
	v_mfma_f32_16x16x32_bf16 v[40:43], v[166:169], v[194:197], v[40:43]
	v_mfma_f32_16x16x32_bf16 v[32:35], v[174:177], v[194:197], v[32:35]
	v_mfma_f32_16x16x32_bf16 v[24:27], v[166:169], v[202:205], v[24:27]
	v_mfma_f32_16x16x32_bf16 v[16:19], v[174:177], v[202:205], v[16:19]
	v_mfma_f32_16x16x32_bf16 v[8:11], v[166:169], v[210:213], v[8:11]
	v_mfma_f32_16x16x32_bf16 v[0:3], v[174:177], v[210:213], v[0:3]
	v_mfma_f32_16x16x32_bf16 v[56:59], v[170:173], v[186:189], v[56:59]
	v_mfma_f32_16x16x32_bf16 v[48:51], v[178:181], v[186:189], v[48:51]
	v_mfma_f32_16x16x32_bf16 v[40:43], v[170:173], v[198:201], v[40:43]
	v_mfma_f32_16x16x32_bf16 v[32:35], v[178:181], v[198:201], v[32:35]
	v_mfma_f32_16x16x32_bf16 v[24:27], v[170:173], v[206:209], v[24:27]
	v_mfma_f32_16x16x32_bf16 v[16:19], v[178:181], v[206:209], v[16:19]
	v_mfma_f32_16x16x32_bf16 v[8:11], v[170:173], v[214:217], v[8:11]
	v_mfma_f32_16x16x32_bf16 v[0:3], v[178:181], v[214:217], v[0:3]
	s_setprio 0
	s_barrier
	s_add_i32 s49, s49, 2
	s_add_u32 s22, s22, 0x100
	s_addc_u32 s23, s23, 0
	s_add_u32 s47, s47, 0x100
	s_addc_u32 s48, s48, 0
	s_cmp_gt_u32 s49, 29
	s_cbranch_scc0 .LBB0_985
	s_and_b64 vcc, exec, s[10:11]
	s_cbranch_vccz .LBB0_988
	s_barrier

; #define PG8_STAGE(bufoff, gbase, voff) do { _Pragma("unroll") for (int _i = 0; _i < 2; ++_i) \
;         __builtin_amdgcn_global_load_lds((const unsigned*)((const char*)(gbase) + (voff)[_i]), (LAS unsigned*)(lds + (bufoff) + ldsw + _i * 8192), 16, 0, 0); } while (0)
; #define PG8_LDA(dst, b, h) do { _Pragma("unroll") for (int m = 0; m < 4; ++m) _Pragma("unroll") for (int k = 0; k < 2; ++k) dst[m][k] = *(const LAS bf16x8*)(lds + PG8_SA(b, h) + aoff + m * 2048 + k * 1024); } while (0)
; #define PG8_LDB(dst, b, h) do { _Pragma("unroll") for (int n = 0; n < 2; ++n) _Pragma("unroll") for (int k = 0; k < 2; ++k) dst[n][k] = *(const LAS bf16x8*)(lds + PG8_SB(b, h) + boff + n * 2048 + k * 1024); } while (0)
; #define PG8_MMA(ai, bj, At, Bt) do { __builtin_amdgcn_s_setprio(1); _Pragma("unroll") for (int m = 0; m < 4; ++m) _Pragma("unroll") for (int n = 0; n < 2; ++n) _Pragma("unroll") for (int k = 0; k < 2; ++k) \
;         acc[ai][bj][m][n] = __builtin_amdgcn_mfma_f32_16x16x32_bf16(Bt[n][k], At[m][k], acc[ai][bj][m][n], 0, 0, 0); __builtin_amdgcn_s_setprio(0); } while (0)
; #define PG8_WAIT_V(n) asm volatile("s_waitcnt vmcnt(" #n ")" ::: "memory")
; #define PG8_WAIT_L(n) asm volatile("s_waitcnt lgkmcnt(" #n ")" ::: "memory")
; #define PG8_BAR __builtin_amdgcn_s_barrier()
; template <class Epi, class Sched = StaticOrder, class EpiSub = NoSub, bool FAST = false>
; __device__ __forceinline__ void gemm_phase(LAS unsigned char* lds, const Gemm g, const Sched& S, const Epi& E, const EpiSub& ES = EpiSub()) {
;     ...
;             const bool last = (t == nt - 2);
;             const char* a1 = cA + (size_t)(t + 1) * kstep;
;             const char* a2 = last ? nA : cA + (size_t)(t + 2) * kstep; const char* b2 = last ? nB : cB + (size_t)(t + 2) * kstep;
;             const char* a3 = a2 + kstep; const char* b3 = b2 + kstep;
;             if constexpr (FAST && PG8_SP2) {
;             PG8_LDB(B0, 0, 0); PG8_LDB(B1, 0, 1); PG8_SCHED; PG8_LDA(At, 0, 0); PG8_STAGE(PG8_SA(1, 1), a1 + hstepA, voffA);
;             PG8_WAIT_V(8); PG8_WAIT_L(0); PG8_BAR; PG8_MMA(0, 0, At, B0); PG8_MMA(0, 1, At, B1); PG8_BAR; PG8_SCHED;
;             PG8_LDA(At, 0, 1); PG8_STAGE(PG8_SB(0, 0), b2, voffB); PG8_STAGE(PG8_SB(0, 1), b2 + hstepB, voffB); PG8_STAGE(PG8_SA(0, 0), a2, voffA);
;             PG8_WAIT_V(8); PG8_WAIT_L(0); PG8_BAR; PG8_MMA(1, 0, At, B0); PG8_MMA(1, 1, At, B1); PG8_BAR; PG8_SCHED;
.LBB0_1079:
	ds_read_b128 v[96:99], v201
	ds_read_b128 v[100:103], v201 offset:1024
	ds_read_b128 v[108:111], v201 offset:2048
	ds_read_b128 v[116:119], v201 offset:3072
	ds_read_b128 v[144:147], v202
	ds_read_b128 v[148:151], v202 offset:1024
	ds_read_b128 v[152:155], v202 offset:2048
	ds_read_b128 v[156:159], v202 offset:3072
	s_add_i32 s85, s46, 2
	s_add_u32 s44, s42, 0xffea0080
	s_addc_u32 s45, s43, -1
	s_cmp_eq_u32 s71, s46
	s_cselect_b32 s46, s38, s44
	s_cselect_b32 s47, s39, s45
	s_cselect_b32 s45, s41, s84
	s_cselect_b32 s44, s40, s83
	v_lshl_add_u64 v[190:191], s[42:43], 0, v[176:177]
	s_add_i32 m0, s48, 0xc000
	ds_read_b128 v[160:163], v203
	ds_read_b128 v[164:167], v203 offset:1024
	ds_read_b128 v[182:185], v203 offset:2048
	ds_read_b128 v[186:189], v203 offset:3072
	ds_read_b128 v[194:197], v203 offset:4096
	ds_read_b128 v[204:207], v203 offset:5120
	ds_read_b128 v[208:211], v203 offset:6144
	ds_read_b128 v[212:215], v203 offset:7168
	global_load_lds_dwordx4 v[190:191], off
	v_lshl_add_u64 v[190:191], s[42:43], 0, v[178:179]
	s_add_i32 m0, s48, 0xe000
	s_nop 0
	global_load_lds_dwordx4 v[190:191], off
	s_waitcnt vmcnt(8)
	s_waitcnt lgkmcnt(0)
	s_barrier
	s_setprio 1
	v_mfma_f32_16x16x32_bf16 v[140:143], v[96:99], v[160:163], v[140:143]
	v_mfma_f32_16x16x32_bf16 v[136:139], v[108:111], v[160:163], v[136:139]
	v_mfma_f32_16x16x32_bf16 v[124:127], v[96:99], v[182:185], v[124:127]
	v_mfma_f32_16x16x32_bf16 v[120:123], v[108:111], v[182:185], v[120:123]
	v_mfma_f32_16x16x32_bf16 v[92:95], v[96:99], v[194:197], v[92:95]
	v_mfma_f32_16x16x32_bf16 v[88:91], v[108:111], v[194:197], v[88:91]
	v_mfma_f32_16x16x32_bf16 v[76:79], v[96:99], v[208:211], v[76:79]
	v_mfma_f32_16x16x32_bf16 v[72:75], v[108:111], v[208:211], v[72:75]
	v_mfma_f32_16x16x32_bf16 v[140:143], v[100:103], v[164:167], v[140:143]
	v_mfma_f32_16x16x32_bf16 v[136:139], v[116:119], v[164:167], v[136:139]
	v_mfma_f32_16x16x32_bf16 v[124:127], v[100:103], v[186:189], v[124:127]
	v_mfma_f32_16x16x32_bf16 v[120:123], v[116:119], v[186:189], v[120:123]
	v_mfma_f32_16x16x32_bf16 v[92:95], v[100:103], v[204:207], v[92:95]
	v_mfma_f32_16x16x32_bf16 v[88:91], v[116:119], v[204:207], v[88:91]
	v_mfma_f32_16x16x32_bf16 v[76:79], v[100:103], v[212:215], v[76:79]
	v_mfma_f32_16x16x32_bf16 v[72:75], v[116:119], v[212:215], v[72:75]
	v_mfma_f32_16x16x32_bf16 v[132:135], v[144:147], v[160:163], v[132:135]
	v_mfma_f32_16x16x32_bf16 v[128:131], v[152:155], v[160:163], v[128:131]
	v_mfma_f32_16x16x32_bf16 v[112:115], v[144:147], v[182:185], v[112:115]
	v_mfma_f32_16x16x32_bf16 v[104:107], v[152:155], v[182:185], v[104:107]
	v_mfma_f32_16x16x32_bf16 v[84:87], v[144:147], v[194:197], v[84:87]
	v_mfma_f32_16x16x32_bf16 v[80:83], v[152:155], v[194:197], v[80:83]
	v_mfma_f32_16x16x32_bf16 v[68:71], v[144:147], v[208:211], v[68:71]
	v_mfma_f32_16x16x32_bf16 v[64:67], v[152:155], v[208:211], v[64:67]
	v_mfma_f32_16x16x32_bf16 v[132:135], v[148:151], v[164:167], v[132:135]
	v_mfma_f32_16x16x32_bf16 v[128:131], v[156:159], v[164:167], v[128:131]
	v_mfma_f32_16x16x32_bf16 v[112:115], v[148:151], v[186:189], v[112:115]
	v_mfma_f32_16x16x32_bf16 v[104:107], v[156:159], v[186:189], v[104:107]
	v_mfma_f32_16x16x32_bf16 v[84:87], v[148:151], v[204:207], v[84:87]
	v_mfma_f32_16x16x32_bf16 v[80:83], v[156:159], v[204:207], v[80:83]
	v_mfma_f32_16x16x32_bf16 v[68:71], v[148:151], v[212:215], v[68:71]
	v_mfma_f32_16x16x32_bf16 v[64:67], v[156:159], v[212:215], v[64:67]
	s_setprio 0
	s_barrier
	s_add_i32 s86, s58, s27
	v_lshl_add_u64 v[190:191], s[44:45], 0, v[170:171]
	s_mov_b32 m0, s86
	ds_read_b128 v[160:163], v203 offset:16384
	ds_read_b128 v[164:167], v203 offset:17408
	ds_read_b128 v[182:185], v203 offset:18432
	ds_read_b128 v[186:189], v203 offset:19456
	ds_read_b128 v[194:197], v203 offset:20480
	ds_read_b128 v[204:207], v203 offset:21504
	ds_read_b128 v[208:211], v203 offset:22528
	ds_read_b128 v[212:215], v203 offset:23552
	global_load_lds_dwordx4 v[190:191], off
	s_add_i32 m0, s86, 0x2000
	s_add_u32 s86, s44, 0x160000
	v_lshl_add_u64 v[216:217], s[44:45], 0, v[174:175]
	s_addc_u32 s87, s45, 0
	s_add_i32 s88, s59, s27
	global_load_lds_dwordx4 v[216:217], off
	v_lshl_add_u64 v[218:219], s[86:87], 0, v[170:171]
	s_mov_b32 m0, s88
	v_lshl_add_u64 v[220:221], s[46:47], 0, v[172:173]
	global_load_lds_dwordx4 v[218:219], off
	v_lshl_add_u64 v[218:219], s[86:87], 0, v[174:175]
	s_add_i32 m0, s88, 0x2000
	s_nop 0
	global_load_lds_dwordx4 v[218:219], off
	v_lshl_add_u64 v[218:219], s[46:47], 0, v[168:169]
	s_mov_b32 m0, s48
	s_nop 0
	global_load_lds_dwordx4 v[218:219], off
	s_mov_b32 m0, s49
	s_nop 0
	global_load_lds_dwordx4 v[220:221], off
	s_waitcnt vmcnt(8)
	s_waitcnt lgkmcnt(0)
	s_barrier
; #define PG8_STAGE(bufoff, gbase, voff) do { _Pragma("unroll") for (int _i = 0; _i < 2; ++_i) \
;         __builtin_amdgcn_global_load_lds((const unsigned*)((const char*)(gbase) + (voff)[_i]), (LAS unsigned*)(lds + (bufoff) + ldsw + _i * 8192), 16, 0, 0); } while (0)
; #define PG8_LDA(dst, b, h) do { _Pragma("unroll") for (int m = 0; m < 4; ++m) _Pragma("unroll") for (int k = 0; k < 2; ++k) dst[m][k] = *(const LAS bf16x8*)(lds + PG8_SA(b, h) + aoff + m * 2048 + k * 1024); } while (0)
; #define PG8_LDB(dst, b, h) do { _Pragma("unroll") for (int n = 0; n < 2; ++n) _Pragma("unroll") for (int k = 0; k < 2; ++k) dst[n][k] = *(const LAS bf16x8*)(lds + PG8_SB(b, h) + boff + n * 2048 + k * 1024); } while (0)
; #define PG8_MMA(ai, bj, At, Bt) do { __builtin_amdgcn_s_setprio(1); _Pragma("unroll") for (int m = 0; m < 4; ++m) _Pragma("unroll") for (int n = 0; n < 2; ++n) _Pragma("unroll") for (int k = 0; k < 2; ++k) \
;         acc[ai][bj][m][n] = __builtin_amdgcn_mfma_f32_16x16x32_bf16(Bt[n][k], At[m][k], acc[ai][bj][m][n], 0, 0, 0); __builtin_amdgcn_s_setprio(0); } while (0)
; #define PG8_WAIT_V(n) asm volatile("s_waitcnt vmcnt(" #n ")" ::: "memory")
; #define PG8_WAIT_L(n) asm volatile("s_waitcnt lgkmcnt(" #n ")" ::: "memory")
; #define PG8_BAR __builtin_amdgcn_s_barrier()
; #define PG8_SCHED __builtin_amdgcn_sched_barrier(0)
; template <class Epi, class Sched = StaticOrder, class EpiSub = NoSub, bool FAST = false>
; __device__ __forceinline__ void gemm_phase(LAS unsigned char* lds, const Gemm g, const Sched& S, const Epi& E, const EpiSub& ES = EpiSub()) {
;     ...
;             PG8_WAIT_V(8); PG8_WAIT_L(0); PG8_BAR; PG8_MMA(1, 0, At, B0); PG8_MMA(1, 1, At, B1); PG8_BAR; PG8_SCHED;
;             PG8_LDB(B0, 1, 0); PG8_LDB(B1, 1, 1); PG8_SCHED; PG8_LDA(At, 1, 0); PG8_STAGE(PG8_SA(0, 1), a2 + hstepA, voffA);
;             PG8_WAIT_V(8); PG8_WAIT_L(0); PG8_BAR; PG8_MMA(0, 0, At, B0); PG8_MMA(0, 1, At, B1); PG8_BAR; PG8_SCHED;
	s_setprio 1
	v_mfma_f32_16x16x32_bf16 v[60:63], v[96:99], v[160:163], v[60:63]
	v_mfma_f32_16x16x32_bf16 v[56:59], v[108:111], v[160:163], v[56:59]
	v_mfma_f32_16x16x32_bf16 v[44:47], v[96:99], v[182:185], v[44:47]
	v_mfma_f32_16x16x32_bf16 v[40:43], v[108:111], v[182:185], v[40:43]
	v_mfma_f32_16x16x32_bf16 v[28:31], v[96:99], v[194:197], v[28:31]
	v_mfma_f32_16x16x32_bf16 v[24:27], v[108:111], v[194:197], v[24:27]
	v_mfma_f32_16x16x32_bf16 v[12:15], v[96:99], v[208:211], v[12:15]
	v_mfma_f32_16x16x32_bf16 v[8:11], v[108:111], v[208:211], v[8:11]
	v_mfma_f32_16x16x32_bf16 v[60:63], v[100:103], v[164:167], v[60:63]
	v_mfma_f32_16x16x32_bf16 v[56:59], v[116:119], v[164:167], v[56:59]
	v_mfma_f32_16x16x32_bf16 v[44:47], v[100:103], v[186:189], v[44:47]
	v_mfma_f32_16x16x32_bf16 v[40:43], v[116:119], v[186:189], v[40:43]
	v_mfma_f32_16x16x32_bf16 v[28:31], v[100:103], v[204:207], v[28:31]
	v_mfma_f32_16x16x32_bf16 v[24:27], v[116:119], v[204:207], v[24:27]
	v_mfma_f32_16x16x32_bf16 v[12:15], v[100:103], v[212:215], v[12:15]
	v_mfma_f32_16x16x32_bf16 v[8:11], v[116:119], v[212:215], v[8:11]
	v_mfma_f32_16x16x32_bf16 v[52:55], v[144:147], v[160:163], v[52:55]
	v_mfma_f32_16x16x32_bf16 v[48:51], v[152:155], v[160:163], v[48:51]
	v_mfma_f32_16x16x32_bf16 v[36:39], v[144:147], v[182:185], v[36:39]
	v_mfma_f32_16x16x32_bf16 v[32:35], v[152:155], v[182:185], v[32:35]
	v_mfma_f32_16x16x32_bf16 v[20:23], v[144:147], v[194:197], v[20:23]
	v_mfma_f32_16x16x32_bf16 v[16:19], v[152:155], v[194:197], v[16:19]
	v_mfma_f32_16x16x32_bf16 v[4:7], v[144:147], v[208:211], v[4:7]
	v_mfma_f32_16x16x32_bf16 v[0:3], v[152:155], v[208:211], v[0:3]
	v_mfma_f32_16x16x32_bf16 v[52:55], v[148:151], v[164:167], v[52:55]
	v_mfma_f32_16x16x32_bf16 v[48:51], v[156:159], v[164:167], v[48:51]
	v_mfma_f32_16x16x32_bf16 v[36:39], v[148:151], v[186:189], v[36:39]
	v_mfma_f32_16x16x32_bf16 v[32:35], v[156:159], v[186:189], v[32:35]
	v_mfma_f32_16x16x32_bf16 v[20:23], v[148:151], v[204:207], v[20:23]
	v_mfma_f32_16x16x32_bf16 v[16:19], v[156:159], v[204:207], v[16:19]
	v_mfma_f32_16x16x32_bf16 v[4:7], v[148:151], v[212:215], v[4:7]
	v_mfma_f32_16x16x32_bf16 v[0:3], v[156:159], v[212:215], v[0:3]
	s_setprio 0
	s_barrier
	s_add_i32 s86, 0, 0x18000
	s_add_i32 s87, 0, 0x1c000
	v_add_u32_e32 v116, s86, v198
	v_add_u32_e32 v156, s87, v198
	ds_read_b128 v[96:99], v116
	ds_read_b128 v[100:103], v116 offset:1024
	ds_read_b128 v[108:111], v116 offset:2048
	ds_read_b128 v[116:119], v116 offset:3072
	ds_read_b128 v[144:147], v156
	ds_read_b128 v[148:151], v156 offset:1024
	ds_read_b128 v[152:155], v156 offset:2048
	ds_read_b128 v[156:159], v156 offset:3072
	s_add_u32 s46, s46, 0x160000
	s_addc_u32 s47, s47, 0
	s_mov_b32 m0, s50
	v_lshl_add_u64 v[222:223], s[46:47], 0, v[168:169]
	ds_read_b128 v[160:163], v203 offset:32768
	ds_read_b128 v[164:167], v203 offset:33792
	ds_read_b128 v[182:185], v203 offset:34816
	ds_read_b128 v[186:189], v203 offset:35840
	ds_read_b128 v[194:197], v203 offset:36864
	ds_read_b128 v[204:207], v203 offset:37888
	ds_read_b128 v[208:211], v203 offset:38912
	ds_read_b128 v[212:215], v203 offset:39936
	global_load_lds_dwordx4 v[222:223], off
	v_lshl_add_u64 v[222:223], s[46:47], 0, v[172:173]
	s_mov_b32 m0, s51
	s_nop 0
	global_load_lds_dwordx4 v[222:223], off
	s_waitcnt vmcnt(8)
	s_waitcnt lgkmcnt(0)
	s_barrier
	s_setprio 1
	v_mfma_f32_16x16x32_bf16 v[140:143], v[96:99], v[160:163], v[140:143]
	v_mfma_f32_16x16x32_bf16 v[136:139], v[108:111], v[160:163], v[136:139]
	v_mfma_f32_16x16x32_bf16 v[124:127], v[96:99], v[182:185], v[124:127]
	v_mfma_f32_16x16x32_bf16 v[120:123], v[108:111], v[182:185], v[120:123]
	v_mfma_f32_16x16x32_bf16 v[92:95], v[96:99], v[194:197], v[92:95]
	v_mfma_f32_16x16x32_bf16 v[88:91], v[108:111], v[194:197], v[88:91]
	v_mfma_f32_16x16x32_bf16 v[76:79], v[96:99], v[208:211], v[76:79]
	v_mfma_f32_16x16x32_bf16 v[72:75], v[108:111], v[208:211], v[72:75]
	v_mfma_f32_16x16x32_bf16 v[140:143], v[100:103], v[164:167], v[140:143]
	v_mfma_f32_16x16x32_bf16 v[136:139], v[116:119], v[164:167], v[136:139]
	v_mfma_f32_16x16x32_bf16 v[124:127], v[100:103], v[186:189], v[124:127]
	v_mfma_f32_16x16x32_bf16 v[120:123], v[116:119], v[186:189], v[120:123]
	v_mfma_f32_16x16x32_bf16 v[92:95], v[100:103], v[204:207], v[92:95]
	v_mfma_f32_16x16x32_bf16 v[88:91], v[116:119], v[204:207], v[88:91]
	v_mfma_f32_16x16x32_bf16 v[76:79], v[100:103], v[212:215], v[76:79]
	v_mfma_f32_16x16x32_bf16 v[72:75], v[116:119], v[212:215], v[72:75]
	v_mfma_f32_16x16x32_bf16 v[132:135], v[144:147], v[160:163], v[132:135]
	v_mfma_f32_16x16x32_bf16 v[128:131], v[152:155], v[160:163], v[128:131]
	v_mfma_f32_16x16x32_bf16 v[112:115], v[144:147], v[182:185], v[112:115]
	v_mfma_f32_16x16x32_bf16 v[104:107], v[152:155], v[182:185], v[104:107]
	v_mfma_f32_16x16x32_bf16 v[84:87], v[144:147], v[194:197], v[84:87]
	v_mfma_f32_16x16x32_bf16 v[80:83], v[152:155], v[194:197], v[80:83]
	v_mfma_f32_16x16x32_bf16 v[68:71], v[144:147], v[208:211], v[68:71]
	v_mfma_f32_16x16x32_bf16 v[64:67], v[152:155], v[208:211], v[64:67]
	v_mfma_f32_16x16x32_bf16 v[132:135], v[148:151], v[164:167], v[132:135]
	v_mfma_f32_16x16x32_bf16 v[128:131], v[156:159], v[164:167], v[128:131]
	v_mfma_f32_16x16x32_bf16 v[112:115], v[148:151], v[186:189], v[112:115]
	v_mfma_f32_16x16x32_bf16 v[104:107], v[156:159], v[186:189], v[104:107]
	v_mfma_f32_16x16x32_bf16 v[84:87], v[148:151], v[204:207], v[84:87]
	v_mfma_f32_16x16x32_bf16 v[80:83], v[156:159], v[204:207], v[80:83]
	v_mfma_f32_16x16x32_bf16 v[68:71], v[148:151], v[212:215], v[68:71]
	v_mfma_f32_16x16x32_bf16 v[64:67], v[156:159], v[212:215], v[64:67]
	s_setprio 0
	s_barrier
; #define PG8_STAGE(bufoff, gbase, voff) do { _Pragma("unroll") for (int _i = 0; _i < 2; ++_i) \
;         __builtin_amdgcn_global_load_lds((const unsigned*)((const char*)(gbase) + (voff)[_i]), (LAS unsigned*)(lds + (bufoff) + ldsw + _i * 8192), 16, 0, 0); } while (0)
; #define PG8_LDA(dst, b, h) do { _Pragma("unroll") for (int m = 0; m < 4; ++m) _Pragma("unroll") for (int k = 0; k < 2; ++k) dst[m][k] = *(const LAS bf16x8*)(lds + PG8_SA(b, h) + aoff + m * 2048 + k * 1024); } while (0)
; #define PG8_MMA(ai, bj, At, Bt) do { __builtin_amdgcn_s_setprio(1); _Pragma("unroll") for (int m = 0; m < 4; ++m) _Pragma("unroll") for (int n = 0; n < 2; ++n) _Pragma("unroll") for (int k = 0; k < 2; ++k) \
;         acc[ai][bj][m][n] = __builtin_amdgcn_mfma_f32_16x16x32_bf16(Bt[n][k], At[m][k], acc[ai][bj][m][n], 0, 0, 0); __builtin_amdgcn_s_setprio(0); } while (0)
; #define PG8_WAIT_V(n) asm volatile("s_waitcnt vmcnt(" #n ")" ::: "memory")
; #define PG8_WAIT_L(n) asm volatile("s_waitcnt lgkmcnt(" #n ")" ::: "memory")
; #define PG8_BAR __builtin_amdgcn_s_barrier()
; #define PG8_SCHED __builtin_amdgcn_sched_barrier(0)
; template <class Epi, class Sched = StaticOrder, class EpiSub = NoSub, bool FAST = false>
; __device__ __forceinline__ void gemm_phase(LAS unsigned char* lds, const Gemm g, const Sched& S, const Epi& E, const EpiSub& ES = EpiSub()) {
;     ...
;         for (int t = 0; t < nt; t += 2) {
;     ...
;             PG8_LDA(At, 1, 1); PG8_STAGE(PG8_SB(1, 0), b3, voffB); PG8_STAGE(PG8_SB(1, 1), b3 + hstepB, voffB); PG8_STAGE(PG8_SA(1, 0), a3, voffA);
;             PG8_WAIT_V(8); PG8_WAIT_L(0); PG8_BAR; PG8_MMA(1, 0, At, B0); PG8_MMA(1, 1, At, B1); PG8_BAR; PG8_SCHED;
	s_add_i32 s46, s86, s27
	v_lshl_add_u64 v[190:191], v[190:191], 0, s[16:17]
	s_mov_b32 m0, s46
	ds_read_b128 v[160:163], v203 offset:49152
	ds_read_b128 v[164:167], v203 offset:50176
	ds_read_b128 v[182:185], v203 offset:51200
	ds_read_b128 v[186:189], v203 offset:52224
	ds_read_b128 v[194:197], v203 offset:53248
	ds_read_b128 v[204:207], v203 offset:54272
	ds_read_b128 v[208:211], v203 offset:55296
	ds_read_b128 v[212:215], v203 offset:56320
	global_load_lds_dwordx4 v[190:191], off
	s_add_i32 m0, s46, 0x2000
	s_add_u32 s44, s44, 0x160080
	v_lshl_add_u64 v[190:191], v[216:217], 0, s[16:17]
	s_addc_u32 s45, s45, 0
	s_add_i32 s46, s87, s27
	global_load_lds_dwordx4 v[190:191], off
	v_lshl_add_u64 v[190:191], s[44:45], 0, v[170:171]
	s_mov_b32 m0, s46
	s_nop 0
	global_load_lds_dwordx4 v[190:191], off
	v_lshl_add_u64 v[190:191], s[44:45], 0, v[174:175]
	s_add_i32 m0, s46, 0x2000
	s_nop 0
	global_load_lds_dwordx4 v[190:191], off
	v_lshl_add_u64 v[190:191], v[218:219], 0, s[16:17]
	s_mov_b32 m0, s53
	s_nop 0
	global_load_lds_dwordx4 v[190:191], off
	v_lshl_add_u64 v[190:191], v[220:221], 0, s[16:17]
	s_mov_b32 m0, s54
	s_nop 0
	global_load_lds_dwordx4 v[190:191], off
	s_waitcnt vmcnt(8)
	s_waitcnt lgkmcnt(0)
	s_barrier
	s_setprio 1
	v_mfma_f32_16x16x32_bf16 v[60:63], v[96:99], v[160:163], v[60:63]
	v_mfma_f32_16x16x32_bf16 v[56:59], v[108:111], v[160:163], v[56:59]
	v_mfma_f32_16x16x32_bf16 v[44:47], v[96:99], v[182:185], v[44:47]
	v_mfma_f32_16x16x32_bf16 v[40:43], v[108:111], v[182:185], v[40:43]
	v_mfma_f32_16x16x32_bf16 v[28:31], v[96:99], v[194:197], v[28:31]
	v_mfma_f32_16x16x32_bf16 v[24:27], v[108:111], v[194:197], v[24:27]
	v_mfma_f32_16x16x32_bf16 v[12:15], v[96:99], v[208:211], v[12:15]
	v_mfma_f32_16x16x32_bf16 v[8:11], v[108:111], v[208:211], v[8:11]
	v_mfma_f32_16x16x32_bf16 v[60:63], v[100:103], v[164:167], v[60:63]
	v_mfma_f32_16x16x32_bf16 v[56:59], v[116:119], v[164:167], v[56:59]
	v_mfma_f32_16x16x32_bf16 v[44:47], v[100:103], v[186:189], v[44:47]
	v_mfma_f32_16x16x32_bf16 v[40:43], v[116:119], v[186:189], v[40:43]
	v_mfma_f32_16x16x32_bf16 v[28:31], v[100:103], v[204:207], v[28:31]
	v_mfma_f32_16x16x32_bf16 v[24:27], v[116:119], v[204:207], v[24:27]
	v_mfma_f32_16x16x32_bf16 v[12:15], v[100:103], v[212:215], v[12:15]
	v_mfma_f32_16x16x32_bf16 v[8:11], v[116:119], v[212:215], v[8:11]
	v_mfma_f32_16x16x32_bf16 v[52:55], v[144:147], v[160:163], v[52:55]
	v_mfma_f32_16x16x32_bf16 v[48:51], v[152:155], v[160:163], v[48:51]
	v_mfma_f32_16x16x32_bf16 v[36:39], v[144:147], v[182:185], v[36:39]
	v_mfma_f32_16x16x32_bf16 v[32:35], v[152:155], v[182:185], v[32:35]
	v_mfma_f32_16x16x32_bf16 v[20:23], v[144:147], v[194:197], v[20:23]
	v_mfma_f32_16x16x32_bf16 v[16:19], v[152:155], v[194:197], v[16:19]
	v_mfma_f32_16x16x32_bf16 v[4:7], v[144:147], v[208:211], v[4:7]
	v_mfma_f32_16x16x32_bf16 v[0:3], v[152:155], v[208:211], v[0:3]
	v_mfma_f32_16x16x32_bf16 v[52:55], v[148:151], v[164:167], v[52:55]
	v_mfma_f32_16x16x32_bf16 v[48:51], v[156:159], v[164:167], v[48:51]
	v_mfma_f32_16x16x32_bf16 v[36:39], v[148:151], v[186:189], v[36:39]
	v_mfma_f32_16x16x32_bf16 v[32:35], v[156:159], v[186:189], v[32:35]
	v_mfma_f32_16x16x32_bf16 v[20:23], v[148:151], v[204:207], v[20:23]
	v_mfma_f32_16x16x32_bf16 v[16:19], v[156:159], v[204:207], v[16:19]
	v_mfma_f32_16x16x32_bf16 v[4:7], v[148:151], v[212:215], v[4:7]
	v_mfma_f32_16x16x32_bf16 v[0:3], v[156:159], v[212:215], v[0:3]
	s_setprio 0
	s_barrier
	s_add_u32 s42, s42, 0x100
	s_addc_u32 s43, s43, 0
	s_add_u32 s83, s83, 0x100
	s_addc_u32 s84, s84, 0
	s_cmp_ge_u32 s85, s70
	s_mov_b32 s46, s85
	s_cbranch_scc0 .LBB0_1079
	s_and_b64 vcc, exec, s[18:19]
	s_cbranch_vccz .LBB0_1082
	s_barrier
